# y computed as S_t.r_t on the updated state, pipelined into the next step: no c1/c2 scalar terms, 6 LDS reads per step; producer stores r instead of dec*r
# speedup vs baseline: 1.0181x; 1.0181x over previous
; template <int CTRL> __device__ __forceinline__ float dpp_f(float x) { return __int_as_float(__builtin_amdgcn_update_dpp(0, __float_as_int(x), CTRL, 0xf, 0xf, false)); }
; __device__ __forceinline__ void p8_scan(const Args& a, LAS unsigned char* lds) {
;     ...
;                 for (int tt = 0; tt < TC; ++tt) {
;                     ScanOps n; scan_ld(n, bt + (tt + 1 < TC ? tt + 1 : tt) * SPITCH, jq4, myrow);
;                     __builtin_amdgcn_sched_barrier(0);
;                     f32x2 ta = S01 * o.al.lo, ty = S01 * o.wr.lo; ta = S23 * o.al.hi + ta; ty = S23 * o.wr.hi + ty;
;                     float pa = ta.x + ta.y, py = ty.x + ty.y;
;                     f32x2 kv01 = o.kv.lo * o.vi, kv23 = o.kv.hi * o.vi;
;     ...
;                     asm volatile("" : "+v"(kv01), "+v"(kv23), "+v"(vc));
;                     pa += dpp_f<0x121>(pa); py += dpp_f<0x121>(py); pa += dpp_f<0x122>(pa); py += dpp_f<0x122>(py);
;                     pa += dpp_f<0x124>(pa); pa += dpp_f<0x128>(pa);
;                     S01 = S01 * o.wv.lo + (o.be.lo * pa + kv01);
;                     S23 = S23 * o.wv.hi + (o.be.hi * pa + kv23);
;     ...
;                     __builtin_amdgcn_sched_barrier(0);
;                     o = n;
.LBB0_1090:
	s_and_b32 s43, s14, 1
	s_mul_i32 s52, s43, 0xc400
	s_lshl_b32 s43, s43, 13
	v_lshl_add_u32 v38, v27, 2, s52
	v_lshl_add_u32 v39, v1, 2, s52
	v_mov_b32_e32 v40, s52
	v_add_u32_e32 v41, s43, v123
	v_cndmask_b32_e64 v41, v124, v41, s[2:3]
	ds_read_b128 v[10:13], v38 offset:512
	ds_read_b128 v[6:9], v38 offset:256
	ds_read_b32 v28, v39 offset:1280
	ds_read_b128 v[2:5], v38 offset:0
	ds_read_b128 v[14:17], v38 offset:768
	ds_read_b128 v[18:21], v38 offset:1024
	s_waitcnt lgkmcnt(3)
	ds_read_b128 v[50:53], v38 offset:2080
	ds_read_b128 v[46:49], v38 offset:1824
	ds_read_b32 v62, v39 offset:2848
	ds_read_b128 v[42:45], v38 offset:1568
	ds_read_b128 v[54:57], v38 offset:2336
	ds_read_b128 v[58:61], v38 offset:2592
	v_pk_mul_f32 v[34:35], v[22:23], v[10:11]
	v_pk_fma_f32 v[34:35], v[24:25], v[12:13], v[34:35]
	v_add_f32_e32 v34, v34, v35
	v_pk_mul_f32 v[6:7], v[6:7], v[28:29] op_sel_hi:[1,0]
	v_pk_mul_f32 v[8:9], v[8:9], v[28:29] op_sel_hi:[1,0]
	v_add_f32_dpp v34, v34, v34 row_ror:1 row_mask:0xf bank_mask:0xf bound_ctrl:1
	s_waitcnt lgkmcnt(7)
	v_pk_fma_f32 v[6:7], v[22:23], v[2:3], v[6:7]
	v_pk_fma_f32 v[8:9], v[24:25], v[4:5], v[8:9]
	v_add_f32_dpp v34, v34, v34 row_ror:2 row_mask:0xf bank_mask:0xf bound_ctrl:1
	s_nop 0
	s_nop 0
	v_add_f32_dpp v34, v34, v34 row_ror:4 row_mask:0xf bank_mask:0xf bound_ctrl:1
	s_nop 0
	s_nop 0
	v_add_f32_dpp v34, v34, v34 row_ror:8 row_mask:0xf bank_mask:0xf bound_ctrl:1
	v_pk_fma_f32 v[22:23], v[14:15], v[34:35], v[6:7] op_sel_hi:[1,0,1]
	v_pk_fma_f32 v[24:25], v[16:17], v[34:35], v[8:9] op_sel_hi:[1,0,1]
	s_waitcnt lgkmcnt(3)
	v_pk_mul_f32 v[36:37], v[22:23], v[18:19]
	v_pk_fma_f32 v[36:37], v[24:25], v[20:21], v[36:37]
	ds_read_b128 v[10:13], v38 offset:3648
	ds_read_b128 v[6:9], v38 offset:3392
	ds_read_b32 v28, v39 offset:4416
	ds_read_b128 v[2:5], v38 offset:3136
	ds_read_b128 v[14:17], v38 offset:3904
	ds_read_b128 v[18:21], v38 offset:4160
	v_pk_mul_f32 v[34:35], v[22:23], v[50:51]
	v_pk_fma_f32 v[34:35], v[24:25], v[52:53], v[34:35]
	v_add_f32_e32 v34, v34, v35
	v_add_f32_e32 v36, v36, v37
	v_pk_mul_f32 v[46:47], v[46:47], v[62:63] op_sel_hi:[1,0]
	v_add_f32_dpp v34, v34, v34 row_ror:1 row_mask:0xf bank_mask:0xf bound_ctrl:1
	v_add_f32_dpp v36, v36, v36 row_ror:1 row_mask:0xf bank_mask:0xf bound_ctrl:1
	s_waitcnt lgkmcnt(7)
	v_pk_fma_f32 v[46:47], v[22:23], v[42:43], v[46:47]
	v_add_f32_dpp v34, v34, v34 row_ror:2 row_mask:0xf bank_mask:0xf bound_ctrl:1
	v_add_f32_dpp v36, v36, v36 row_ror:2 row_mask:0xf bank_mask:0xf bound_ctrl:1
	v_pk_mul_f32 v[48:49], v[48:49], v[62:63] op_sel_hi:[1,0]
	v_add_f32_dpp v34, v34, v34 row_ror:4 row_mask:0xf bank_mask:0xf bound_ctrl:1
	v_pk_fma_f32 v[48:49], v[24:25], v[44:45], v[48:49]
	s_nop 0
	v_add_f32_dpp v34, v34, v34 row_ror:8 row_mask:0xf bank_mask:0xf bound_ctrl:1
	v_pk_fma_f32 v[22:23], v[54:55], v[34:35], v[46:47] op_sel_hi:[1,0,1]
	v_pk_fma_f32 v[24:25], v[56:57], v[34:35], v[48:49] op_sel_hi:[1,0,1]
	s_waitcnt lgkmcnt(3)
	v_pk_mul_f32 v[66:67], v[22:23], v[58:59]
	v_pk_fma_f32 v[66:67], v[24:25], v[60:61], v[66:67]
	ds_read_b128 v[50:53], v38 offset:5216
	ds_read_b128 v[46:49], v38 offset:4960
	ds_read_b32 v62, v39 offset:5984
	ds_read_b128 v[42:45], v38 offset:4704
	ds_read_b128 v[54:57], v38 offset:5472
	ds_read_b128 v[58:61], v38 offset:5728
	v_pk_mul_f32 v[34:35], v[22:23], v[10:11]
	v_pk_fma_f32 v[34:35], v[24:25], v[12:13], v[34:35]
	v_add_f32_e32 v34, v34, v35
	v_add_f32_e32 v66, v66, v67
	v_pk_mul_f32 v[6:7], v[6:7], v[28:29] op_sel_hi:[1,0]
	v_add_f32_dpp v34, v34, v34 row_ror:1 row_mask:0xf bank_mask:0xf bound_ctrl:1
	v_add_f32_dpp v66, v66, v66 row_ror:1 row_mask:0xf bank_mask:0xf bound_ctrl:1
	s_waitcnt lgkmcnt(7)
	v_pk_fma_f32 v[6:7], v[22:23], v[2:3], v[6:7]
	v_add_f32_dpp v34, v34, v34 row_ror:2 row_mask:0xf bank_mask:0xf bound_ctrl:1
	v_add_f32_dpp v66, v66, v66 row_ror:2 row_mask:0xf bank_mask:0xf bound_ctrl:1
	v_pk_mul_f32 v[8:9], v[8:9], v[28:29] op_sel_hi:[1,0]
	v_add_f32_dpp v34, v34, v34 row_ror:4 row_mask:0xf bank_mask:0xf bound_ctrl:1
	v_pk_fma_f32 v[8:9], v[24:25], v[4:5], v[8:9]
	ds_write2st64_b32 v41, v36, v66 offset0:0 offset1:1
	v_add_f32_dpp v34, v34, v34 row_ror:8 row_mask:0xf bank_mask:0xf bound_ctrl:1
	v_pk_fma_f32 v[22:23], v[14:15], v[34:35], v[6:7] op_sel_hi:[1,0,1]
	v_pk_fma_f32 v[24:25], v[16:17], v[34:35], v[8:9] op_sel_hi:[1,0,1]
	s_waitcnt lgkmcnt(4)
	v_pk_mul_f32 v[36:37], v[22:23], v[18:19]
	v_pk_fma_f32 v[36:37], v[24:25], v[20:21], v[36:37]
	ds_read_b128 v[10:13], v38 offset:6784
	ds_read_b128 v[6:9], v38 offset:6528
	ds_read_b32 v28, v39 offset:7552
	ds_read_b128 v[2:5], v38 offset:6272
	ds_read_b128 v[14:17], v38 offset:7040
	ds_read_b128 v[18:21], v38 offset:7296
	v_pk_mul_f32 v[34:35], v[22:23], v[50:51]
	v_pk_fma_f32 v[34:35], v[24:25], v[52:53], v[34:35]
	v_add_f32_e32 v34, v34, v35
	v_add_f32_e32 v36, v36, v37
	v_pk_mul_f32 v[46:47], v[46:47], v[62:63] op_sel_hi:[1,0]
	v_add_f32_dpp v34, v34, v34 row_ror:1 row_mask:0xf bank_mask:0xf bound_ctrl:1
	v_add_f32_dpp v36, v36, v36 row_ror:1 row_mask:0xf bank_mask:0xf bound_ctrl:1
	s_waitcnt lgkmcnt(8)
	v_pk_fma_f32 v[46:47], v[22:23], v[42:43], v[46:47]
	v_add_f32_dpp v34, v34, v34 row_ror:2 row_mask:0xf bank_mask:0xf bound_ctrl:1
	v_add_f32_dpp v36, v36, v36 row_ror:2 row_mask:0xf bank_mask:0xf bound_ctrl:1
	v_pk_mul_f32 v[48:49], v[48:49], v[62:63] op_sel_hi:[1,0]
	v_add_f32_dpp v34, v34, v34 row_ror:4 row_mask:0xf bank_mask:0xf bound_ctrl:1
	v_pk_fma_f32 v[48:49], v[24:25], v[44:45], v[48:49]
	s_nop 0
	v_add_f32_dpp v34, v34, v34 row_ror:8 row_mask:0xf bank_mask:0xf bound_ctrl:1
	v_pk_fma_f32 v[22:23], v[54:55], v[34:35], v[46:47] op_sel_hi:[1,0,1]
	v_pk_fma_f32 v[24:25], v[56:57], v[34:35], v[48:49] op_sel_hi:[1,0,1]
	s_waitcnt lgkmcnt(3)
; template <int CTRL> __device__ __forceinline__ float dpp_f(float x) { return __int_as_float(__builtin_amdgcn_update_dpp(0, __float_as_int(x), CTRL, 0xf, 0xf, false)); }
; __device__ __forceinline__ void p8_scan(const Args& a, LAS unsigned char* lds) {
;     ...
;                 for (int tt = 0; tt < TC; ++tt) {
;                     ScanOps n; scan_ld(n, bt + (tt + 1 < TC ? tt + 1 : tt) * SPITCH, jq4, myrow);
;                     __builtin_amdgcn_sched_barrier(0);
;                     f32x2 ta = S01 * o.al.lo, ty = S01 * o.wr.lo; ta = S23 * o.al.hi + ta; ty = S23 * o.wr.hi + ty;
;                     float pa = ta.x + ta.y, py = ty.x + ty.y;
;                     f32x2 kv01 = o.kv.lo * o.vi, kv23 = o.kv.hi * o.vi;
;     ...
;                     asm volatile("" : "+v"(kv01), "+v"(kv23), "+v"(vc));
;                     pa += dpp_f<0x121>(pa); py += dpp_f<0x121>(py); pa += dpp_f<0x122>(pa); py += dpp_f<0x122>(py);
;                     pa += dpp_f<0x124>(pa); pa += dpp_f<0x128>(pa);
;                     S01 = S01 * o.wv.lo + (o.be.lo * pa + kv01);
;                     S23 = S23 * o.wv.hi + (o.be.hi * pa + kv23);
;     ...
;                     __builtin_amdgcn_sched_barrier(0);
;                     o = n;
	v_pk_mul_f32 v[66:67], v[22:23], v[58:59]
	v_pk_fma_f32 v[66:67], v[24:25], v[60:61], v[66:67]
	ds_read_b128 v[50:53], v38 offset:8352
	ds_read_b128 v[46:49], v38 offset:8096
	ds_read_b32 v62, v39 offset:9120
	ds_read_b128 v[42:45], v38 offset:7840
	ds_read_b128 v[54:57], v38 offset:8608
	ds_read_b128 v[58:61], v38 offset:8864
	v_pk_mul_f32 v[34:35], v[22:23], v[10:11]
	v_pk_fma_f32 v[34:35], v[24:25], v[12:13], v[34:35]
	v_add_f32_e32 v34, v34, v35
	v_add_f32_e32 v66, v66, v67
	v_pk_mul_f32 v[6:7], v[6:7], v[28:29] op_sel_hi:[1,0]
	v_add_f32_dpp v34, v34, v34 row_ror:1 row_mask:0xf bank_mask:0xf bound_ctrl:1
	v_add_f32_dpp v66, v66, v66 row_ror:1 row_mask:0xf bank_mask:0xf bound_ctrl:1
	s_waitcnt lgkmcnt(7)
	v_pk_fma_f32 v[6:7], v[22:23], v[2:3], v[6:7]
	v_add_f32_dpp v34, v34, v34 row_ror:2 row_mask:0xf bank_mask:0xf bound_ctrl:1
	v_add_f32_dpp v66, v66, v66 row_ror:2 row_mask:0xf bank_mask:0xf bound_ctrl:1
	v_pk_mul_f32 v[8:9], v[8:9], v[28:29] op_sel_hi:[1,0]
	v_add_f32_dpp v34, v34, v34 row_ror:4 row_mask:0xf bank_mask:0xf bound_ctrl:1
	v_pk_fma_f32 v[8:9], v[24:25], v[4:5], v[8:9]
	ds_write2st64_b32 v41, v36, v66 offset0:2 offset1:3
	v_add_f32_dpp v34, v34, v34 row_ror:8 row_mask:0xf bank_mask:0xf bound_ctrl:1
	v_pk_fma_f32 v[22:23], v[14:15], v[34:35], v[6:7] op_sel_hi:[1,0,1]
	v_pk_fma_f32 v[24:25], v[16:17], v[34:35], v[8:9] op_sel_hi:[1,0,1]
	s_waitcnt lgkmcnt(4)
	v_pk_mul_f32 v[36:37], v[22:23], v[18:19]
	v_pk_fma_f32 v[36:37], v[24:25], v[20:21], v[36:37]
	ds_read_b128 v[10:13], v38 offset:9920
	ds_read_b128 v[6:9], v38 offset:9664
	ds_read_b32 v28, v39 offset:10688
	ds_read_b128 v[2:5], v38 offset:9408
	ds_read_b128 v[14:17], v38 offset:10176
	ds_read_b128 v[18:21], v38 offset:10432
	v_pk_mul_f32 v[34:35], v[22:23], v[50:51]
	v_pk_fma_f32 v[34:35], v[24:25], v[52:53], v[34:35]
	v_add_f32_e32 v34, v34, v35
	v_add_f32_e32 v36, v36, v37
	v_pk_mul_f32 v[46:47], v[46:47], v[62:63] op_sel_hi:[1,0]
	v_add_f32_dpp v34, v34, v34 row_ror:1 row_mask:0xf bank_mask:0xf bound_ctrl:1
	v_add_f32_dpp v36, v36, v36 row_ror:1 row_mask:0xf bank_mask:0xf bound_ctrl:1
	s_waitcnt lgkmcnt(8)
	v_pk_fma_f32 v[46:47], v[22:23], v[42:43], v[46:47]
	v_add_f32_dpp v34, v34, v34 row_ror:2 row_mask:0xf bank_mask:0xf bound_ctrl:1
	v_add_f32_dpp v36, v36, v36 row_ror:2 row_mask:0xf bank_mask:0xf bound_ctrl:1
	v_pk_mul_f32 v[48:49], v[48:49], v[62:63] op_sel_hi:[1,0]
	v_add_f32_dpp v34, v34, v34 row_ror:4 row_mask:0xf bank_mask:0xf bound_ctrl:1
	v_pk_fma_f32 v[48:49], v[24:25], v[44:45], v[48:49]
	s_nop 0
	v_add_f32_dpp v34, v34, v34 row_ror:8 row_mask:0xf bank_mask:0xf bound_ctrl:1
	v_pk_fma_f32 v[22:23], v[54:55], v[34:35], v[46:47] op_sel_hi:[1,0,1]
	v_pk_fma_f32 v[24:25], v[56:57], v[34:35], v[48:49] op_sel_hi:[1,0,1]
	s_waitcnt lgkmcnt(3)
	v_pk_mul_f32 v[66:67], v[22:23], v[58:59]
	v_pk_fma_f32 v[66:67], v[24:25], v[60:61], v[66:67]
	ds_read_b128 v[50:53], v38 offset:11488
	ds_read_b128 v[46:49], v38 offset:11232
	ds_read_b32 v62, v39 offset:12256
	ds_read_b128 v[42:45], v38 offset:10976
	ds_read_b128 v[54:57], v38 offset:11744
	ds_read_b128 v[58:61], v38 offset:12000
	v_pk_mul_f32 v[34:35], v[22:23], v[10:11]
	v_pk_fma_f32 v[34:35], v[24:25], v[12:13], v[34:35]
	v_add_f32_e32 v34, v34, v35
	v_add_f32_e32 v66, v66, v67
	v_pk_mul_f32 v[6:7], v[6:7], v[28:29] op_sel_hi:[1,0]
	v_add_f32_dpp v34, v34, v34 row_ror:1 row_mask:0xf bank_mask:0xf bound_ctrl:1
	v_add_f32_dpp v66, v66, v66 row_ror:1 row_mask:0xf bank_mask:0xf bound_ctrl:1
	s_waitcnt lgkmcnt(7)
	v_pk_fma_f32 v[6:7], v[22:23], v[2:3], v[6:7]
	v_add_f32_dpp v34, v34, v34 row_ror:2 row_mask:0xf bank_mask:0xf bound_ctrl:1
	v_add_f32_dpp v66, v66, v66 row_ror:2 row_mask:0xf bank_mask:0xf bound_ctrl:1
	v_pk_mul_f32 v[8:9], v[8:9], v[28:29] op_sel_hi:[1,0]
	v_add_f32_dpp v34, v34, v34 row_ror:4 row_mask:0xf bank_mask:0xf bound_ctrl:1
	v_pk_fma_f32 v[8:9], v[24:25], v[4:5], v[8:9]
	ds_write2st64_b32 v41, v36, v66 offset0:4 offset1:5
	v_add_f32_dpp v34, v34, v34 row_ror:8 row_mask:0xf bank_mask:0xf bound_ctrl:1
	v_pk_fma_f32 v[22:23], v[14:15], v[34:35], v[6:7] op_sel_hi:[1,0,1]
	v_pk_fma_f32 v[24:25], v[16:17], v[34:35], v[8:9] op_sel_hi:[1,0,1]
	s_waitcnt lgkmcnt(4)
	v_pk_mul_f32 v[36:37], v[22:23], v[18:19]
	v_pk_fma_f32 v[36:37], v[24:25], v[20:21], v[36:37]
	ds_read_b128 v[10:13], v38 offset:13056
	ds_read_b128 v[6:9], v38 offset:12800
	ds_read_b32 v28, v39 offset:13824
	ds_read_b128 v[2:5], v38 offset:12544
	ds_read_b128 v[14:17], v38 offset:13312
	ds_read_b128 v[18:21], v38 offset:13568
	v_pk_mul_f32 v[34:35], v[22:23], v[50:51]
	v_pk_fma_f32 v[34:35], v[24:25], v[52:53], v[34:35]
	v_add_f32_e32 v34, v34, v35
	v_add_f32_e32 v36, v36, v37
	v_pk_mul_f32 v[46:47], v[46:47], v[62:63] op_sel_hi:[1,0]
	v_add_f32_dpp v34, v34, v34 row_ror:1 row_mask:0xf bank_mask:0xf bound_ctrl:1
	v_add_f32_dpp v36, v36, v36 row_ror:1 row_mask:0xf bank_mask:0xf bound_ctrl:1
	s_waitcnt lgkmcnt(8)
	v_pk_fma_f32 v[46:47], v[22:23], v[42:43], v[46:47]
	v_add_f32_dpp v34, v34, v34 row_ror:2 row_mask:0xf bank_mask:0xf bound_ctrl:1
	v_add_f32_dpp v36, v36, v36 row_ror:2 row_mask:0xf bank_mask:0xf bound_ctrl:1
	v_pk_mul_f32 v[48:49], v[48:49], v[62:63] op_sel_hi:[1,0]
	v_add_f32_dpp v34, v34, v34 row_ror:4 row_mask:0xf bank_mask:0xf bound_ctrl:1
	v_pk_fma_f32 v[48:49], v[24:25], v[44:45], v[48:49]
	s_nop 0
	v_add_f32_dpp v34, v34, v34 row_ror:8 row_mask:0xf bank_mask:0xf bound_ctrl:1
	v_pk_fma_f32 v[22:23], v[54:55], v[34:35], v[46:47] op_sel_hi:[1,0,1]
	v_pk_fma_f32 v[24:25], v[56:57], v[34:35], v[48:49] op_sel_hi:[1,0,1]
	s_waitcnt lgkmcnt(3)
; template <int CTRL> __device__ __forceinline__ float dpp_f(float x) { return __int_as_float(__builtin_amdgcn_update_dpp(0, __float_as_int(x), CTRL, 0xf, 0xf, false)); }
; __device__ __forceinline__ void p8_scan(const Args& a, LAS unsigned char* lds) {
;     ...
;                 for (int tt = 0; tt < TC; ++tt) {
;                     ScanOps n; scan_ld(n, bt + (tt + 1 < TC ? tt + 1 : tt) * SPITCH, jq4, myrow);
;                     __builtin_amdgcn_sched_barrier(0);
;                     f32x2 ta = S01 * o.al.lo, ty = S01 * o.wr.lo; ta = S23 * o.al.hi + ta; ty = S23 * o.wr.hi + ty;
;                     float pa = ta.x + ta.y, py = ty.x + ty.y;
;                     f32x2 kv01 = o.kv.lo * o.vi, kv23 = o.kv.hi * o.vi;
;     ...
;                     asm volatile("" : "+v"(kv01), "+v"(kv23), "+v"(vc));
;                     pa += dpp_f<0x121>(pa); py += dpp_f<0x121>(py); pa += dpp_f<0x122>(pa); py += dpp_f<0x122>(py);
;                     pa += dpp_f<0x124>(pa); pa += dpp_f<0x128>(pa);
;                     S01 = S01 * o.wv.lo + (o.be.lo * pa + kv01);
;                     S23 = S23 * o.wv.hi + (o.be.hi * pa + kv23);
;     ...
;                     __builtin_amdgcn_sched_barrier(0);
;                     o = n;
	v_pk_mul_f32 v[66:67], v[22:23], v[58:59]
	v_pk_fma_f32 v[66:67], v[24:25], v[60:61], v[66:67]
	ds_read_b128 v[50:53], v38 offset:14624
	ds_read_b128 v[46:49], v38 offset:14368
	ds_read_b32 v62, v39 offset:15392
	ds_read_b128 v[42:45], v38 offset:14112
	ds_read_b128 v[54:57], v38 offset:14880
	ds_read_b128 v[58:61], v38 offset:15136
	v_pk_mul_f32 v[34:35], v[22:23], v[10:11]
	v_pk_fma_f32 v[34:35], v[24:25], v[12:13], v[34:35]
	v_add_f32_e32 v34, v34, v35
	v_add_f32_e32 v66, v66, v67
	v_pk_mul_f32 v[6:7], v[6:7], v[28:29] op_sel_hi:[1,0]
	v_add_f32_dpp v34, v34, v34 row_ror:1 row_mask:0xf bank_mask:0xf bound_ctrl:1
	v_add_f32_dpp v66, v66, v66 row_ror:1 row_mask:0xf bank_mask:0xf bound_ctrl:1
	s_waitcnt lgkmcnt(7)
	v_pk_fma_f32 v[6:7], v[22:23], v[2:3], v[6:7]
	v_add_f32_dpp v34, v34, v34 row_ror:2 row_mask:0xf bank_mask:0xf bound_ctrl:1
	v_add_f32_dpp v66, v66, v66 row_ror:2 row_mask:0xf bank_mask:0xf bound_ctrl:1
	v_pk_mul_f32 v[8:9], v[8:9], v[28:29] op_sel_hi:[1,0]
	v_add_f32_dpp v34, v34, v34 row_ror:4 row_mask:0xf bank_mask:0xf bound_ctrl:1
	v_pk_fma_f32 v[8:9], v[24:25], v[4:5], v[8:9]
	ds_write2st64_b32 v41, v36, v66 offset0:6 offset1:7
	v_add_f32_dpp v34, v34, v34 row_ror:8 row_mask:0xf bank_mask:0xf bound_ctrl:1
	v_pk_fma_f32 v[22:23], v[14:15], v[34:35], v[6:7] op_sel_hi:[1,0,1]
	v_pk_fma_f32 v[24:25], v[16:17], v[34:35], v[8:9] op_sel_hi:[1,0,1]
	s_waitcnt lgkmcnt(4)
	v_pk_mul_f32 v[36:37], v[22:23], v[18:19]
	v_pk_fma_f32 v[36:37], v[24:25], v[20:21], v[36:37]
	ds_read_b128 v[10:13], v38 offset:16192
	ds_read_b128 v[6:9], v38 offset:15936
	ds_read_b32 v28, v39 offset:16960
	ds_read_b128 v[2:5], v38 offset:15680
	ds_read_b128 v[14:17], v38 offset:16448
	ds_read_b128 v[18:21], v38 offset:16704
	v_pk_mul_f32 v[34:35], v[22:23], v[50:51]
	v_pk_fma_f32 v[34:35], v[24:25], v[52:53], v[34:35]
	v_add_f32_e32 v34, v34, v35
	v_add_f32_e32 v36, v36, v37
	v_pk_mul_f32 v[46:47], v[46:47], v[62:63] op_sel_hi:[1,0]
	v_add_f32_dpp v34, v34, v34 row_ror:1 row_mask:0xf bank_mask:0xf bound_ctrl:1
	v_add_f32_dpp v36, v36, v36 row_ror:1 row_mask:0xf bank_mask:0xf bound_ctrl:1
	s_waitcnt lgkmcnt(8)
	v_pk_fma_f32 v[46:47], v[22:23], v[42:43], v[46:47]
	v_add_f32_dpp v34, v34, v34 row_ror:2 row_mask:0xf bank_mask:0xf bound_ctrl:1
	v_add_f32_dpp v36, v36, v36 row_ror:2 row_mask:0xf bank_mask:0xf bound_ctrl:1
	v_pk_mul_f32 v[48:49], v[48:49], v[62:63] op_sel_hi:[1,0]
	v_add_f32_dpp v34, v34, v34 row_ror:4 row_mask:0xf bank_mask:0xf bound_ctrl:1
	v_pk_fma_f32 v[48:49], v[24:25], v[44:45], v[48:49]
	s_nop 0
	v_add_f32_dpp v34, v34, v34 row_ror:8 row_mask:0xf bank_mask:0xf bound_ctrl:1
	v_pk_fma_f32 v[22:23], v[54:55], v[34:35], v[46:47] op_sel_hi:[1,0,1]
	v_pk_fma_f32 v[24:25], v[56:57], v[34:35], v[48:49] op_sel_hi:[1,0,1]
	s_waitcnt lgkmcnt(3)
	v_pk_mul_f32 v[66:67], v[22:23], v[58:59]
	v_pk_fma_f32 v[66:67], v[24:25], v[60:61], v[66:67]
	ds_read_b128 v[50:53], v38 offset:17760
	ds_read_b128 v[46:49], v38 offset:17504
	ds_read_b32 v62, v39 offset:18528
	ds_read_b128 v[42:45], v38 offset:17248
	ds_read_b128 v[54:57], v38 offset:18016
	ds_read_b128 v[58:61], v38 offset:18272
	v_pk_mul_f32 v[34:35], v[22:23], v[10:11]
	v_pk_fma_f32 v[34:35], v[24:25], v[12:13], v[34:35]
	v_add_f32_e32 v34, v34, v35
	v_add_f32_e32 v66, v66, v67
	v_pk_mul_f32 v[6:7], v[6:7], v[28:29] op_sel_hi:[1,0]
	v_add_f32_dpp v34, v34, v34 row_ror:1 row_mask:0xf bank_mask:0xf bound_ctrl:1
	v_add_f32_dpp v66, v66, v66 row_ror:1 row_mask:0xf bank_mask:0xf bound_ctrl:1
	s_waitcnt lgkmcnt(7)
	v_pk_fma_f32 v[6:7], v[22:23], v[2:3], v[6:7]
	v_add_f32_dpp v34, v34, v34 row_ror:2 row_mask:0xf bank_mask:0xf bound_ctrl:1
	v_add_f32_dpp v66, v66, v66 row_ror:2 row_mask:0xf bank_mask:0xf bound_ctrl:1
	v_pk_mul_f32 v[8:9], v[8:9], v[28:29] op_sel_hi:[1,0]
	v_add_f32_dpp v34, v34, v34 row_ror:4 row_mask:0xf bank_mask:0xf bound_ctrl:1
	v_pk_fma_f32 v[8:9], v[24:25], v[4:5], v[8:9]
	ds_write2st64_b32 v41, v36, v66 offset0:8 offset1:9
	v_add_f32_dpp v34, v34, v34 row_ror:8 row_mask:0xf bank_mask:0xf bound_ctrl:1
	v_pk_fma_f32 v[22:23], v[14:15], v[34:35], v[6:7] op_sel_hi:[1,0,1]
	v_pk_fma_f32 v[24:25], v[16:17], v[34:35], v[8:9] op_sel_hi:[1,0,1]
	s_waitcnt lgkmcnt(4)
	v_pk_mul_f32 v[36:37], v[22:23], v[18:19]
	v_pk_fma_f32 v[36:37], v[24:25], v[20:21], v[36:37]
	ds_read_b128 v[10:13], v38 offset:19328
	ds_read_b128 v[6:9], v38 offset:19072
	ds_read_b32 v28, v39 offset:20096
	ds_read_b128 v[2:5], v38 offset:18816
	ds_read_b128 v[14:17], v38 offset:19584
	ds_read_b128 v[18:21], v38 offset:19840
	v_pk_mul_f32 v[34:35], v[22:23], v[50:51]
	v_pk_fma_f32 v[34:35], v[24:25], v[52:53], v[34:35]
	v_add_f32_e32 v34, v34, v35
	v_add_f32_e32 v36, v36, v37
	v_pk_mul_f32 v[46:47], v[46:47], v[62:63] op_sel_hi:[1,0]
	v_add_f32_dpp v34, v34, v34 row_ror:1 row_mask:0xf bank_mask:0xf bound_ctrl:1
	v_add_f32_dpp v36, v36, v36 row_ror:1 row_mask:0xf bank_mask:0xf bound_ctrl:1
	s_waitcnt lgkmcnt(8)
	v_pk_fma_f32 v[46:47], v[22:23], v[42:43], v[46:47]
	v_add_f32_dpp v34, v34, v34 row_ror:2 row_mask:0xf bank_mask:0xf bound_ctrl:1
	v_add_f32_dpp v36, v36, v36 row_ror:2 row_mask:0xf bank_mask:0xf bound_ctrl:1
	v_pk_mul_f32 v[48:49], v[48:49], v[62:63] op_sel_hi:[1,0]
	v_add_f32_dpp v34, v34, v34 row_ror:4 row_mask:0xf bank_mask:0xf bound_ctrl:1
	v_pk_fma_f32 v[48:49], v[24:25], v[44:45], v[48:49]
	s_nop 0
	v_add_f32_dpp v34, v34, v34 row_ror:8 row_mask:0xf bank_mask:0xf bound_ctrl:1
	v_pk_fma_f32 v[22:23], v[54:55], v[34:35], v[46:47] op_sel_hi:[1,0,1]
	v_pk_fma_f32 v[24:25], v[56:57], v[34:35], v[48:49] op_sel_hi:[1,0,1]
	s_waitcnt lgkmcnt(3)
; template <int CTRL> __device__ __forceinline__ float dpp_f(float x) { return __int_as_float(__builtin_amdgcn_update_dpp(0, __float_as_int(x), CTRL, 0xf, 0xf, false)); }
; __device__ __forceinline__ void p8_scan(const Args& a, LAS unsigned char* lds) {
;     ...
;                 for (int tt = 0; tt < TC; ++tt) {
;                     ScanOps n; scan_ld(n, bt + (tt + 1 < TC ? tt + 1 : tt) * SPITCH, jq4, myrow);
;                     __builtin_amdgcn_sched_barrier(0);
;                     f32x2 ta = S01 * o.al.lo, ty = S01 * o.wr.lo; ta = S23 * o.al.hi + ta; ty = S23 * o.wr.hi + ty;
;                     float pa = ta.x + ta.y, py = ty.x + ty.y;
;                     f32x2 kv01 = o.kv.lo * o.vi, kv23 = o.kv.hi * o.vi;
;     ...
;                     asm volatile("" : "+v"(kv01), "+v"(kv23), "+v"(vc));
;                     pa += dpp_f<0x121>(pa); py += dpp_f<0x121>(py); pa += dpp_f<0x122>(pa); py += dpp_f<0x122>(py);
;                     pa += dpp_f<0x124>(pa); pa += dpp_f<0x128>(pa);
;                     S01 = S01 * o.wv.lo + (o.be.lo * pa + kv01);
;                     S23 = S23 * o.wv.hi + (o.be.hi * pa + kv23);
;     ...
;                     __builtin_amdgcn_sched_barrier(0);
;                     o = n;
	v_pk_mul_f32 v[66:67], v[22:23], v[58:59]
	v_pk_fma_f32 v[66:67], v[24:25], v[60:61], v[66:67]
	ds_read_b128 v[50:53], v38 offset:20896
	ds_read_b128 v[46:49], v38 offset:20640
	ds_read_b32 v62, v39 offset:21664
	ds_read_b128 v[42:45], v38 offset:20384
	ds_read_b128 v[54:57], v38 offset:21152
	ds_read_b128 v[58:61], v38 offset:21408
	v_pk_mul_f32 v[34:35], v[22:23], v[10:11]
	v_pk_fma_f32 v[34:35], v[24:25], v[12:13], v[34:35]
	v_add_f32_e32 v34, v34, v35
	v_add_f32_e32 v66, v66, v67
	v_pk_mul_f32 v[6:7], v[6:7], v[28:29] op_sel_hi:[1,0]
	v_add_f32_dpp v34, v34, v34 row_ror:1 row_mask:0xf bank_mask:0xf bound_ctrl:1
	v_add_f32_dpp v66, v66, v66 row_ror:1 row_mask:0xf bank_mask:0xf bound_ctrl:1
	s_waitcnt lgkmcnt(7)
	v_pk_fma_f32 v[6:7], v[22:23], v[2:3], v[6:7]
	v_add_f32_dpp v34, v34, v34 row_ror:2 row_mask:0xf bank_mask:0xf bound_ctrl:1
	v_add_f32_dpp v66, v66, v66 row_ror:2 row_mask:0xf bank_mask:0xf bound_ctrl:1
	v_pk_mul_f32 v[8:9], v[8:9], v[28:29] op_sel_hi:[1,0]
	v_add_f32_dpp v34, v34, v34 row_ror:4 row_mask:0xf bank_mask:0xf bound_ctrl:1
	v_pk_fma_f32 v[8:9], v[24:25], v[4:5], v[8:9]
	ds_write2st64_b32 v41, v36, v66 offset0:10 offset1:11
	v_add_f32_dpp v34, v34, v34 row_ror:8 row_mask:0xf bank_mask:0xf bound_ctrl:1
	v_pk_fma_f32 v[22:23], v[14:15], v[34:35], v[6:7] op_sel_hi:[1,0,1]
	v_pk_fma_f32 v[24:25], v[16:17], v[34:35], v[8:9] op_sel_hi:[1,0,1]
	s_waitcnt lgkmcnt(4)
	v_pk_mul_f32 v[36:37], v[22:23], v[18:19]
	v_pk_fma_f32 v[36:37], v[24:25], v[20:21], v[36:37]
	ds_read_b128 v[10:13], v38 offset:22464
	ds_read_b128 v[6:9], v38 offset:22208
	ds_read_b32 v28, v39 offset:23232
	ds_read_b128 v[2:5], v38 offset:21952
	ds_read_b128 v[14:17], v38 offset:22720
	ds_read_b128 v[18:21], v38 offset:22976
	v_pk_mul_f32 v[34:35], v[22:23], v[50:51]
	v_pk_fma_f32 v[34:35], v[24:25], v[52:53], v[34:35]
	v_add_f32_e32 v34, v34, v35
	v_add_f32_e32 v36, v36, v37
	v_pk_mul_f32 v[46:47], v[46:47], v[62:63] op_sel_hi:[1,0]
	v_add_f32_dpp v34, v34, v34 row_ror:1 row_mask:0xf bank_mask:0xf bound_ctrl:1
	v_add_f32_dpp v36, v36, v36 row_ror:1 row_mask:0xf bank_mask:0xf bound_ctrl:1
	s_waitcnt lgkmcnt(8)
	v_pk_fma_f32 v[46:47], v[22:23], v[42:43], v[46:47]
	v_add_f32_dpp v34, v34, v34 row_ror:2 row_mask:0xf bank_mask:0xf bound_ctrl:1
	v_add_f32_dpp v36, v36, v36 row_ror:2 row_mask:0xf bank_mask:0xf bound_ctrl:1
	v_pk_mul_f32 v[48:49], v[48:49], v[62:63] op_sel_hi:[1,0]
	v_add_f32_dpp v34, v34, v34 row_ror:4 row_mask:0xf bank_mask:0xf bound_ctrl:1
	v_pk_fma_f32 v[48:49], v[24:25], v[44:45], v[48:49]
	s_nop 0
	v_add_f32_dpp v34, v34, v34 row_ror:8 row_mask:0xf bank_mask:0xf bound_ctrl:1
	v_pk_fma_f32 v[22:23], v[54:55], v[34:35], v[46:47] op_sel_hi:[1,0,1]
	v_pk_fma_f32 v[24:25], v[56:57], v[34:35], v[48:49] op_sel_hi:[1,0,1]
	s_waitcnt lgkmcnt(3)
	v_pk_mul_f32 v[66:67], v[22:23], v[58:59]
	v_pk_fma_f32 v[66:67], v[24:25], v[60:61], v[66:67]
	ds_read_b128 v[50:53], v38 offset:24032
	ds_read_b128 v[46:49], v38 offset:23776
	ds_read_b32 v62, v39 offset:24800
	ds_read_b128 v[42:45], v38 offset:23520
	ds_read_b128 v[54:57], v38 offset:24288
	ds_read_b128 v[58:61], v38 offset:24544
	v_pk_mul_f32 v[34:35], v[22:23], v[10:11]
	v_pk_fma_f32 v[34:35], v[24:25], v[12:13], v[34:35]
	v_add_f32_e32 v34, v34, v35
	v_add_f32_e32 v66, v66, v67
	v_pk_mul_f32 v[6:7], v[6:7], v[28:29] op_sel_hi:[1,0]
	v_add_f32_dpp v34, v34, v34 row_ror:1 row_mask:0xf bank_mask:0xf bound_ctrl:1
	v_add_f32_dpp v66, v66, v66 row_ror:1 row_mask:0xf bank_mask:0xf bound_ctrl:1
	s_waitcnt lgkmcnt(7)
	v_pk_fma_f32 v[6:7], v[22:23], v[2:3], v[6:7]
	v_add_f32_dpp v34, v34, v34 row_ror:2 row_mask:0xf bank_mask:0xf bound_ctrl:1
	v_add_f32_dpp v66, v66, v66 row_ror:2 row_mask:0xf bank_mask:0xf bound_ctrl:1
	v_pk_mul_f32 v[8:9], v[8:9], v[28:29] op_sel_hi:[1,0]
	v_add_f32_dpp v34, v34, v34 row_ror:4 row_mask:0xf bank_mask:0xf bound_ctrl:1
	v_pk_fma_f32 v[8:9], v[24:25], v[4:5], v[8:9]
	ds_write2st64_b32 v41, v36, v66 offset0:12 offset1:13
	v_add_f32_dpp v34, v34, v34 row_ror:8 row_mask:0xf bank_mask:0xf bound_ctrl:1
	v_pk_fma_f32 v[22:23], v[14:15], v[34:35], v[6:7] op_sel_hi:[1,0,1]
	v_pk_fma_f32 v[24:25], v[16:17], v[34:35], v[8:9] op_sel_hi:[1,0,1]
	s_waitcnt lgkmcnt(4)
	v_pk_mul_f32 v[36:37], v[22:23], v[18:19]
	v_pk_fma_f32 v[36:37], v[24:25], v[20:21], v[36:37]
	ds_read_b128 v[10:13], v38 offset:25600
	ds_read_b128 v[6:9], v38 offset:25344
	ds_read_b32 v28, v39 offset:26368
	ds_read_b128 v[2:5], v38 offset:25088
	ds_read_b128 v[14:17], v38 offset:25856
	ds_read_b128 v[18:21], v38 offset:26112
	v_pk_mul_f32 v[34:35], v[22:23], v[50:51]
	v_pk_fma_f32 v[34:35], v[24:25], v[52:53], v[34:35]
	v_add_f32_e32 v34, v34, v35
	v_add_f32_e32 v36, v36, v37
	v_pk_mul_f32 v[46:47], v[46:47], v[62:63] op_sel_hi:[1,0]
	v_add_f32_dpp v34, v34, v34 row_ror:1 row_mask:0xf bank_mask:0xf bound_ctrl:1
	v_add_f32_dpp v36, v36, v36 row_ror:1 row_mask:0xf bank_mask:0xf bound_ctrl:1
	s_waitcnt lgkmcnt(8)
	v_pk_fma_f32 v[46:47], v[22:23], v[42:43], v[46:47]
	v_add_f32_dpp v34, v34, v34 row_ror:2 row_mask:0xf bank_mask:0xf bound_ctrl:1
	v_add_f32_dpp v36, v36, v36 row_ror:2 row_mask:0xf bank_mask:0xf bound_ctrl:1
	v_pk_mul_f32 v[48:49], v[48:49], v[62:63] op_sel_hi:[1,0]
	v_add_f32_dpp v34, v34, v34 row_ror:4 row_mask:0xf bank_mask:0xf bound_ctrl:1
	v_pk_fma_f32 v[48:49], v[24:25], v[44:45], v[48:49]
	s_nop 0
	v_add_f32_dpp v34, v34, v34 row_ror:8 row_mask:0xf bank_mask:0xf bound_ctrl:1
	v_pk_fma_f32 v[22:23], v[54:55], v[34:35], v[46:47] op_sel_hi:[1,0,1]
	v_pk_fma_f32 v[24:25], v[56:57], v[34:35], v[48:49] op_sel_hi:[1,0,1]
	s_waitcnt lgkmcnt(3)
; template <int CTRL> __device__ __forceinline__ float dpp_f(float x) { return __int_as_float(__builtin_amdgcn_update_dpp(0, __float_as_int(x), CTRL, 0xf, 0xf, false)); }
; __device__ __forceinline__ void p8_scan(const Args& a, LAS unsigned char* lds) {
;     ...
;                 for (int tt = 0; tt < TC; ++tt) {
;                     ScanOps n; scan_ld(n, bt + (tt + 1 < TC ? tt + 1 : tt) * SPITCH, jq4, myrow);
;                     __builtin_amdgcn_sched_barrier(0);
;                     f32x2 ta = S01 * o.al.lo, ty = S01 * o.wr.lo; ta = S23 * o.al.hi + ta; ty = S23 * o.wr.hi + ty;
;                     float pa = ta.x + ta.y, py = ty.x + ty.y;
;                     f32x2 kv01 = o.kv.lo * o.vi, kv23 = o.kv.hi * o.vi;
;     ...
;                     asm volatile("" : "+v"(kv01), "+v"(kv23), "+v"(vc));
;                     pa += dpp_f<0x121>(pa); py += dpp_f<0x121>(py); pa += dpp_f<0x122>(pa); py += dpp_f<0x122>(py);
;                     pa += dpp_f<0x124>(pa); pa += dpp_f<0x128>(pa);
;                     S01 = S01 * o.wv.lo + (o.be.lo * pa + kv01);
;                     S23 = S23 * o.wv.hi + (o.be.hi * pa + kv23);
;     ...
;                     __builtin_amdgcn_sched_barrier(0);
;                     o = n;
	v_pk_mul_f32 v[66:67], v[22:23], v[58:59]
	v_pk_fma_f32 v[66:67], v[24:25], v[60:61], v[66:67]
	ds_read_b128 v[50:53], v38 offset:27168
	ds_read_b128 v[46:49], v38 offset:26912
	ds_read_b32 v62, v39 offset:27936
	ds_read_b128 v[42:45], v38 offset:26656
	ds_read_b128 v[54:57], v38 offset:27424
	ds_read_b128 v[58:61], v38 offset:27680
	v_pk_mul_f32 v[34:35], v[22:23], v[10:11]
	v_pk_fma_f32 v[34:35], v[24:25], v[12:13], v[34:35]
	v_add_f32_e32 v34, v34, v35
	v_add_f32_e32 v66, v66, v67
	v_pk_mul_f32 v[6:7], v[6:7], v[28:29] op_sel_hi:[1,0]
	v_add_f32_dpp v34, v34, v34 row_ror:1 row_mask:0xf bank_mask:0xf bound_ctrl:1
	v_add_f32_dpp v66, v66, v66 row_ror:1 row_mask:0xf bank_mask:0xf bound_ctrl:1
	s_waitcnt lgkmcnt(7)
	v_pk_fma_f32 v[6:7], v[22:23], v[2:3], v[6:7]
	v_add_f32_dpp v34, v34, v34 row_ror:2 row_mask:0xf bank_mask:0xf bound_ctrl:1
	v_add_f32_dpp v66, v66, v66 row_ror:2 row_mask:0xf bank_mask:0xf bound_ctrl:1
	v_pk_mul_f32 v[8:9], v[8:9], v[28:29] op_sel_hi:[1,0]
	v_add_f32_dpp v34, v34, v34 row_ror:4 row_mask:0xf bank_mask:0xf bound_ctrl:1
	v_pk_fma_f32 v[8:9], v[24:25], v[4:5], v[8:9]
	ds_write2st64_b32 v41, v36, v66 offset0:14 offset1:15
	v_add_f32_dpp v34, v34, v34 row_ror:8 row_mask:0xf bank_mask:0xf bound_ctrl:1
	v_pk_fma_f32 v[22:23], v[14:15], v[34:35], v[6:7] op_sel_hi:[1,0,1]
	v_pk_fma_f32 v[24:25], v[16:17], v[34:35], v[8:9] op_sel_hi:[1,0,1]
	s_waitcnt lgkmcnt(4)
	v_pk_mul_f32 v[36:37], v[22:23], v[18:19]
	v_pk_fma_f32 v[36:37], v[24:25], v[20:21], v[36:37]
	ds_read_b128 v[10:13], v38 offset:28736
	ds_read_b128 v[6:9], v38 offset:28480
	ds_read_b32 v28, v39 offset:29504
	ds_read_b128 v[2:5], v38 offset:28224
	ds_read_b128 v[14:17], v38 offset:28992
	ds_read_b128 v[18:21], v38 offset:29248
	v_pk_mul_f32 v[34:35], v[22:23], v[50:51]
	v_pk_fma_f32 v[34:35], v[24:25], v[52:53], v[34:35]
	v_add_f32_e32 v34, v34, v35
	v_add_f32_e32 v36, v36, v37
	v_pk_mul_f32 v[46:47], v[46:47], v[62:63] op_sel_hi:[1,0]
	v_add_f32_dpp v34, v34, v34 row_ror:1 row_mask:0xf bank_mask:0xf bound_ctrl:1
	v_add_f32_dpp v36, v36, v36 row_ror:1 row_mask:0xf bank_mask:0xf bound_ctrl:1
	s_waitcnt lgkmcnt(8)
	v_pk_fma_f32 v[46:47], v[22:23], v[42:43], v[46:47]
	v_add_f32_dpp v34, v34, v34 row_ror:2 row_mask:0xf bank_mask:0xf bound_ctrl:1
	v_add_f32_dpp v36, v36, v36 row_ror:2 row_mask:0xf bank_mask:0xf bound_ctrl:1
	v_pk_mul_f32 v[48:49], v[48:49], v[62:63] op_sel_hi:[1,0]
	v_add_f32_dpp v34, v34, v34 row_ror:4 row_mask:0xf bank_mask:0xf bound_ctrl:1
	v_pk_fma_f32 v[48:49], v[24:25], v[44:45], v[48:49]
	s_nop 0
	v_add_f32_dpp v34, v34, v34 row_ror:8 row_mask:0xf bank_mask:0xf bound_ctrl:1
	v_pk_fma_f32 v[22:23], v[54:55], v[34:35], v[46:47] op_sel_hi:[1,0,1]
	v_pk_fma_f32 v[24:25], v[56:57], v[34:35], v[48:49] op_sel_hi:[1,0,1]
	s_waitcnt lgkmcnt(3)
	v_pk_mul_f32 v[66:67], v[22:23], v[58:59]
	v_pk_fma_f32 v[66:67], v[24:25], v[60:61], v[66:67]
	ds_read_b128 v[50:53], v38 offset:30304
	ds_read_b128 v[46:49], v38 offset:30048
	ds_read_b32 v62, v39 offset:31072
	ds_read_b128 v[42:45], v38 offset:29792
	ds_read_b128 v[54:57], v38 offset:30560
	ds_read_b128 v[58:61], v38 offset:30816
	v_pk_mul_f32 v[34:35], v[22:23], v[10:11]
	v_pk_fma_f32 v[34:35], v[24:25], v[12:13], v[34:35]
	v_add_f32_e32 v34, v34, v35
	v_add_f32_e32 v66, v66, v67
	v_pk_mul_f32 v[6:7], v[6:7], v[28:29] op_sel_hi:[1,0]
	v_add_f32_dpp v34, v34, v34 row_ror:1 row_mask:0xf bank_mask:0xf bound_ctrl:1
	v_add_f32_dpp v66, v66, v66 row_ror:1 row_mask:0xf bank_mask:0xf bound_ctrl:1
	s_waitcnt lgkmcnt(7)
	v_pk_fma_f32 v[6:7], v[22:23], v[2:3], v[6:7]
	v_add_f32_dpp v34, v34, v34 row_ror:2 row_mask:0xf bank_mask:0xf bound_ctrl:1
	v_add_f32_dpp v66, v66, v66 row_ror:2 row_mask:0xf bank_mask:0xf bound_ctrl:1
	v_pk_mul_f32 v[8:9], v[8:9], v[28:29] op_sel_hi:[1,0]
	v_add_f32_dpp v34, v34, v34 row_ror:4 row_mask:0xf bank_mask:0xf bound_ctrl:1
	v_pk_fma_f32 v[8:9], v[24:25], v[4:5], v[8:9]
	ds_write2st64_b32 v41, v36, v66 offset0:16 offset1:17
	v_add_f32_dpp v34, v34, v34 row_ror:8 row_mask:0xf bank_mask:0xf bound_ctrl:1
	v_pk_fma_f32 v[22:23], v[14:15], v[34:35], v[6:7] op_sel_hi:[1,0,1]
	v_pk_fma_f32 v[24:25], v[16:17], v[34:35], v[8:9] op_sel_hi:[1,0,1]
	s_waitcnt lgkmcnt(4)
	v_pk_mul_f32 v[36:37], v[22:23], v[18:19]
	v_pk_fma_f32 v[36:37], v[24:25], v[20:21], v[36:37]
	ds_read_b128 v[10:13], v38 offset:31872
	ds_read_b128 v[6:9], v38 offset:31616
	ds_read_b32 v28, v39 offset:32640
	ds_read_b128 v[2:5], v38 offset:31360
	ds_read_b128 v[14:17], v38 offset:32128
	ds_read_b128 v[18:21], v38 offset:32384
	v_pk_mul_f32 v[34:35], v[22:23], v[50:51]
	v_pk_fma_f32 v[34:35], v[24:25], v[52:53], v[34:35]
	v_add_f32_e32 v34, v34, v35
	v_add_f32_e32 v36, v36, v37
	v_pk_mul_f32 v[46:47], v[46:47], v[62:63] op_sel_hi:[1,0]
	v_add_f32_dpp v34, v34, v34 row_ror:1 row_mask:0xf bank_mask:0xf bound_ctrl:1
	v_add_f32_dpp v36, v36, v36 row_ror:1 row_mask:0xf bank_mask:0xf bound_ctrl:1
	s_waitcnt lgkmcnt(8)
	v_pk_fma_f32 v[46:47], v[22:23], v[42:43], v[46:47]
	v_add_f32_dpp v34, v34, v34 row_ror:2 row_mask:0xf bank_mask:0xf bound_ctrl:1
	v_add_f32_dpp v36, v36, v36 row_ror:2 row_mask:0xf bank_mask:0xf bound_ctrl:1
	v_pk_mul_f32 v[48:49], v[48:49], v[62:63] op_sel_hi:[1,0]
	v_add_f32_dpp v34, v34, v34 row_ror:4 row_mask:0xf bank_mask:0xf bound_ctrl:1
	v_pk_fma_f32 v[48:49], v[24:25], v[44:45], v[48:49]
	s_nop 0
	v_add_f32_dpp v34, v34, v34 row_ror:8 row_mask:0xf bank_mask:0xf bound_ctrl:1
	v_pk_fma_f32 v[22:23], v[54:55], v[34:35], v[46:47] op_sel_hi:[1,0,1]
	v_pk_fma_f32 v[24:25], v[56:57], v[34:35], v[48:49] op_sel_hi:[1,0,1]
	s_waitcnt lgkmcnt(3)
; template <int CTRL> __device__ __forceinline__ float dpp_f(float x) { return __int_as_float(__builtin_amdgcn_update_dpp(0, __float_as_int(x), CTRL, 0xf, 0xf, false)); }
; __device__ __forceinline__ void p8_scan(const Args& a, LAS unsigned char* lds) {
;     ...
;                 for (int tt = 0; tt < TC; ++tt) {
;                     ScanOps n; scan_ld(n, bt + (tt + 1 < TC ? tt + 1 : tt) * SPITCH, jq4, myrow);
;                     __builtin_amdgcn_sched_barrier(0);
;                     f32x2 ta = S01 * o.al.lo, ty = S01 * o.wr.lo; ta = S23 * o.al.hi + ta; ty = S23 * o.wr.hi + ty;
;                     float pa = ta.x + ta.y, py = ty.x + ty.y;
;                     f32x2 kv01 = o.kv.lo * o.vi, kv23 = o.kv.hi * o.vi;
;     ...
;                     asm volatile("" : "+v"(kv01), "+v"(kv23), "+v"(vc));
;                     pa += dpp_f<0x121>(pa); py += dpp_f<0x121>(py); pa += dpp_f<0x122>(pa); py += dpp_f<0x122>(py);
;                     pa += dpp_f<0x124>(pa); pa += dpp_f<0x128>(pa);
;                     S01 = S01 * o.wv.lo + (o.be.lo * pa + kv01);
;                     S23 = S23 * o.wv.hi + (o.be.hi * pa + kv23);
;     ...
;                     __builtin_amdgcn_sched_barrier(0);
;                     o = n;
	v_pk_mul_f32 v[66:67], v[22:23], v[58:59]
	v_pk_fma_f32 v[66:67], v[24:25], v[60:61], v[66:67]
	ds_read_b128 v[50:53], v38 offset:33440
	ds_read_b128 v[46:49], v38 offset:33184
	ds_read_b32 v62, v39 offset:34208
	ds_read_b128 v[42:45], v38 offset:32928
	ds_read_b128 v[54:57], v38 offset:33696
	ds_read_b128 v[58:61], v38 offset:33952
	v_pk_mul_f32 v[34:35], v[22:23], v[10:11]
	v_pk_fma_f32 v[34:35], v[24:25], v[12:13], v[34:35]
	v_add_f32_e32 v34, v34, v35
	v_add_f32_e32 v66, v66, v67
	v_pk_mul_f32 v[6:7], v[6:7], v[28:29] op_sel_hi:[1,0]
	v_add_f32_dpp v34, v34, v34 row_ror:1 row_mask:0xf bank_mask:0xf bound_ctrl:1
	v_add_f32_dpp v66, v66, v66 row_ror:1 row_mask:0xf bank_mask:0xf bound_ctrl:1
	s_waitcnt lgkmcnt(7)
	v_pk_fma_f32 v[6:7], v[22:23], v[2:3], v[6:7]
	v_add_f32_dpp v34, v34, v34 row_ror:2 row_mask:0xf bank_mask:0xf bound_ctrl:1
	v_add_f32_dpp v66, v66, v66 row_ror:2 row_mask:0xf bank_mask:0xf bound_ctrl:1
	v_pk_mul_f32 v[8:9], v[8:9], v[28:29] op_sel_hi:[1,0]
	v_add_f32_dpp v34, v34, v34 row_ror:4 row_mask:0xf bank_mask:0xf bound_ctrl:1
	v_pk_fma_f32 v[8:9], v[24:25], v[4:5], v[8:9]
	ds_write2st64_b32 v41, v36, v66 offset0:18 offset1:19
	v_add_f32_dpp v34, v34, v34 row_ror:8 row_mask:0xf bank_mask:0xf bound_ctrl:1
	v_pk_fma_f32 v[22:23], v[14:15], v[34:35], v[6:7] op_sel_hi:[1,0,1]
	v_pk_fma_f32 v[24:25], v[16:17], v[34:35], v[8:9] op_sel_hi:[1,0,1]
	s_waitcnt lgkmcnt(4)
	v_pk_mul_f32 v[36:37], v[22:23], v[18:19]
	v_pk_fma_f32 v[36:37], v[24:25], v[20:21], v[36:37]
	ds_read_b128 v[10:13], v38 offset:35008
	ds_read_b128 v[6:9], v38 offset:34752
	ds_read_b32 v28, v39 offset:35776
	ds_read_b128 v[2:5], v38 offset:34496
	ds_read_b128 v[14:17], v38 offset:35264
	ds_read_b128 v[18:21], v38 offset:35520
	v_pk_mul_f32 v[34:35], v[22:23], v[50:51]
	v_pk_fma_f32 v[34:35], v[24:25], v[52:53], v[34:35]
	v_add_f32_e32 v34, v34, v35
	v_add_f32_e32 v36, v36, v37
	v_pk_mul_f32 v[46:47], v[46:47], v[62:63] op_sel_hi:[1,0]
	v_add_f32_dpp v34, v34, v34 row_ror:1 row_mask:0xf bank_mask:0xf bound_ctrl:1
	v_add_f32_dpp v36, v36, v36 row_ror:1 row_mask:0xf bank_mask:0xf bound_ctrl:1
	s_waitcnt lgkmcnt(8)
	v_pk_fma_f32 v[46:47], v[22:23], v[42:43], v[46:47]
	v_add_f32_dpp v34, v34, v34 row_ror:2 row_mask:0xf bank_mask:0xf bound_ctrl:1
	v_add_f32_dpp v36, v36, v36 row_ror:2 row_mask:0xf bank_mask:0xf bound_ctrl:1
	v_pk_mul_f32 v[48:49], v[48:49], v[62:63] op_sel_hi:[1,0]
	v_add_f32_dpp v34, v34, v34 row_ror:4 row_mask:0xf bank_mask:0xf bound_ctrl:1
	v_pk_fma_f32 v[48:49], v[24:25], v[44:45], v[48:49]
	s_nop 0
	v_add_f32_dpp v34, v34, v34 row_ror:8 row_mask:0xf bank_mask:0xf bound_ctrl:1
	v_pk_fma_f32 v[22:23], v[54:55], v[34:35], v[46:47] op_sel_hi:[1,0,1]
	v_pk_fma_f32 v[24:25], v[56:57], v[34:35], v[48:49] op_sel_hi:[1,0,1]
	s_waitcnt lgkmcnt(3)
	v_pk_mul_f32 v[66:67], v[22:23], v[58:59]
	v_pk_fma_f32 v[66:67], v[24:25], v[60:61], v[66:67]
	ds_read_b128 v[50:53], v38 offset:36576
	ds_read_b128 v[46:49], v38 offset:36320
	ds_read_b32 v62, v39 offset:37344
	ds_read_b128 v[42:45], v38 offset:36064
	ds_read_b128 v[54:57], v38 offset:36832
	ds_read_b128 v[58:61], v38 offset:37088
	v_pk_mul_f32 v[34:35], v[22:23], v[10:11]
	v_pk_fma_f32 v[34:35], v[24:25], v[12:13], v[34:35]
	v_add_f32_e32 v34, v34, v35
	v_add_f32_e32 v66, v66, v67
	v_pk_mul_f32 v[6:7], v[6:7], v[28:29] op_sel_hi:[1,0]
	v_add_f32_dpp v34, v34, v34 row_ror:1 row_mask:0xf bank_mask:0xf bound_ctrl:1
	v_add_f32_dpp v66, v66, v66 row_ror:1 row_mask:0xf bank_mask:0xf bound_ctrl:1
	s_waitcnt lgkmcnt(7)
	v_pk_fma_f32 v[6:7], v[22:23], v[2:3], v[6:7]
	v_add_f32_dpp v34, v34, v34 row_ror:2 row_mask:0xf bank_mask:0xf bound_ctrl:1
	v_add_f32_dpp v66, v66, v66 row_ror:2 row_mask:0xf bank_mask:0xf bound_ctrl:1
	v_pk_mul_f32 v[8:9], v[8:9], v[28:29] op_sel_hi:[1,0]
	v_add_f32_dpp v34, v34, v34 row_ror:4 row_mask:0xf bank_mask:0xf bound_ctrl:1
	v_pk_fma_f32 v[8:9], v[24:25], v[4:5], v[8:9]
	ds_write2st64_b32 v41, v36, v66 offset0:20 offset1:21
	v_add_f32_dpp v34, v34, v34 row_ror:8 row_mask:0xf bank_mask:0xf bound_ctrl:1
	v_pk_fma_f32 v[22:23], v[14:15], v[34:35], v[6:7] op_sel_hi:[1,0,1]
	v_pk_fma_f32 v[24:25], v[16:17], v[34:35], v[8:9] op_sel_hi:[1,0,1]
	s_waitcnt lgkmcnt(4)
	v_pk_mul_f32 v[36:37], v[22:23], v[18:19]
	v_pk_fma_f32 v[36:37], v[24:25], v[20:21], v[36:37]
	ds_read_b128 v[10:13], v38 offset:38144
	ds_read_b128 v[6:9], v38 offset:37888
	ds_read_b32 v28, v39 offset:38912
	ds_read_b128 v[2:5], v38 offset:37632
	ds_read_b128 v[14:17], v38 offset:38400
	ds_read_b128 v[18:21], v38 offset:38656
	v_pk_mul_f32 v[34:35], v[22:23], v[50:51]
	v_pk_fma_f32 v[34:35], v[24:25], v[52:53], v[34:35]
	v_add_f32_e32 v34, v34, v35
	v_add_f32_e32 v36, v36, v37
	v_pk_mul_f32 v[46:47], v[46:47], v[62:63] op_sel_hi:[1,0]
	v_add_f32_dpp v34, v34, v34 row_ror:1 row_mask:0xf bank_mask:0xf bound_ctrl:1
	v_add_f32_dpp v36, v36, v36 row_ror:1 row_mask:0xf bank_mask:0xf bound_ctrl:1
	s_waitcnt lgkmcnt(8)
	v_pk_fma_f32 v[46:47], v[22:23], v[42:43], v[46:47]
	v_add_f32_dpp v34, v34, v34 row_ror:2 row_mask:0xf bank_mask:0xf bound_ctrl:1
	v_add_f32_dpp v36, v36, v36 row_ror:2 row_mask:0xf bank_mask:0xf bound_ctrl:1
	v_pk_mul_f32 v[48:49], v[48:49], v[62:63] op_sel_hi:[1,0]
	v_add_f32_dpp v34, v34, v34 row_ror:4 row_mask:0xf bank_mask:0xf bound_ctrl:1
	v_pk_fma_f32 v[48:49], v[24:25], v[44:45], v[48:49]
	s_nop 0
	v_add_f32_dpp v34, v34, v34 row_ror:8 row_mask:0xf bank_mask:0xf bound_ctrl:1
	v_pk_fma_f32 v[22:23], v[54:55], v[34:35], v[46:47] op_sel_hi:[1,0,1]
	v_pk_fma_f32 v[24:25], v[56:57], v[34:35], v[48:49] op_sel_hi:[1,0,1]
	s_waitcnt lgkmcnt(3)
; template <int CTRL> __device__ __forceinline__ float dpp_f(float x) { return __int_as_float(__builtin_amdgcn_update_dpp(0, __float_as_int(x), CTRL, 0xf, 0xf, false)); }
; __device__ __forceinline__ void p8_scan(const Args& a, LAS unsigned char* lds) {
;     ...
;                 for (int tt = 0; tt < TC; ++tt) {
;                     ScanOps n; scan_ld(n, bt + (tt + 1 < TC ? tt + 1 : tt) * SPITCH, jq4, myrow);
;                     __builtin_amdgcn_sched_barrier(0);
;                     f32x2 ta = S01 * o.al.lo, ty = S01 * o.wr.lo; ta = S23 * o.al.hi + ta; ty = S23 * o.wr.hi + ty;
;                     float pa = ta.x + ta.y, py = ty.x + ty.y;
;                     f32x2 kv01 = o.kv.lo * o.vi, kv23 = o.kv.hi * o.vi;
;     ...
;                     asm volatile("" : "+v"(kv01), "+v"(kv23), "+v"(vc));
;                     pa += dpp_f<0x121>(pa); py += dpp_f<0x121>(py); pa += dpp_f<0x122>(pa); py += dpp_f<0x122>(py);
;                     pa += dpp_f<0x124>(pa); pa += dpp_f<0x128>(pa);
;                     S01 = S01 * o.wv.lo + (o.be.lo * pa + kv01);
;                     S23 = S23 * o.wv.hi + (o.be.hi * pa + kv23);
;     ...
;                     __builtin_amdgcn_sched_barrier(0);
;                     o = n;
	v_pk_mul_f32 v[66:67], v[22:23], v[58:59]
	v_pk_fma_f32 v[66:67], v[24:25], v[60:61], v[66:67]
	ds_read_b128 v[50:53], v38 offset:39712
	ds_read_b128 v[46:49], v38 offset:39456
	ds_read_b32 v62, v39 offset:40480
	ds_read_b128 v[42:45], v38 offset:39200
	ds_read_b128 v[54:57], v38 offset:39968
	ds_read_b128 v[58:61], v38 offset:40224
	v_pk_mul_f32 v[34:35], v[22:23], v[10:11]
	v_pk_fma_f32 v[34:35], v[24:25], v[12:13], v[34:35]
	v_add_f32_e32 v34, v34, v35
	v_add_f32_e32 v66, v66, v67
	v_pk_mul_f32 v[6:7], v[6:7], v[28:29] op_sel_hi:[1,0]
	v_add_f32_dpp v34, v34, v34 row_ror:1 row_mask:0xf bank_mask:0xf bound_ctrl:1
	v_add_f32_dpp v66, v66, v66 row_ror:1 row_mask:0xf bank_mask:0xf bound_ctrl:1
	s_waitcnt lgkmcnt(7)
	v_pk_fma_f32 v[6:7], v[22:23], v[2:3], v[6:7]
	v_add_f32_dpp v34, v34, v34 row_ror:2 row_mask:0xf bank_mask:0xf bound_ctrl:1
	v_add_f32_dpp v66, v66, v66 row_ror:2 row_mask:0xf bank_mask:0xf bound_ctrl:1
	v_pk_mul_f32 v[8:9], v[8:9], v[28:29] op_sel_hi:[1,0]
	v_add_f32_dpp v34, v34, v34 row_ror:4 row_mask:0xf bank_mask:0xf bound_ctrl:1
	v_pk_fma_f32 v[8:9], v[24:25], v[4:5], v[8:9]
	ds_write2st64_b32 v41, v36, v66 offset0:22 offset1:23
	v_add_f32_dpp v34, v34, v34 row_ror:8 row_mask:0xf bank_mask:0xf bound_ctrl:1
	v_pk_fma_f32 v[22:23], v[14:15], v[34:35], v[6:7] op_sel_hi:[1,0,1]
	v_pk_fma_f32 v[24:25], v[16:17], v[34:35], v[8:9] op_sel_hi:[1,0,1]
	s_waitcnt lgkmcnt(4)
	v_pk_mul_f32 v[36:37], v[22:23], v[18:19]
	v_pk_fma_f32 v[36:37], v[24:25], v[20:21], v[36:37]
	ds_read_b128 v[10:13], v38 offset:41280
	ds_read_b128 v[6:9], v38 offset:41024
	ds_read_b32 v28, v39 offset:42048
	ds_read_b128 v[2:5], v38 offset:40768
	ds_read_b128 v[14:17], v38 offset:41536
	ds_read_b128 v[18:21], v38 offset:41792
	v_pk_mul_f32 v[34:35], v[22:23], v[50:51]
	v_pk_fma_f32 v[34:35], v[24:25], v[52:53], v[34:35]
	v_add_f32_e32 v34, v34, v35
	v_add_f32_e32 v36, v36, v37
	v_pk_mul_f32 v[46:47], v[46:47], v[62:63] op_sel_hi:[1,0]
	v_add_f32_dpp v34, v34, v34 row_ror:1 row_mask:0xf bank_mask:0xf bound_ctrl:1
	v_add_f32_dpp v36, v36, v36 row_ror:1 row_mask:0xf bank_mask:0xf bound_ctrl:1
	s_waitcnt lgkmcnt(8)
	v_pk_fma_f32 v[46:47], v[22:23], v[42:43], v[46:47]
	v_add_f32_dpp v34, v34, v34 row_ror:2 row_mask:0xf bank_mask:0xf bound_ctrl:1
	v_add_f32_dpp v36, v36, v36 row_ror:2 row_mask:0xf bank_mask:0xf bound_ctrl:1
	v_pk_mul_f32 v[48:49], v[48:49], v[62:63] op_sel_hi:[1,0]
	v_add_f32_dpp v34, v34, v34 row_ror:4 row_mask:0xf bank_mask:0xf bound_ctrl:1
	v_pk_fma_f32 v[48:49], v[24:25], v[44:45], v[48:49]
	s_nop 0
	v_add_f32_dpp v34, v34, v34 row_ror:8 row_mask:0xf bank_mask:0xf bound_ctrl:1
	v_pk_fma_f32 v[22:23], v[54:55], v[34:35], v[46:47] op_sel_hi:[1,0,1]
	v_pk_fma_f32 v[24:25], v[56:57], v[34:35], v[48:49] op_sel_hi:[1,0,1]
	s_waitcnt lgkmcnt(3)
	v_pk_mul_f32 v[66:67], v[22:23], v[58:59]
	v_pk_fma_f32 v[66:67], v[24:25], v[60:61], v[66:67]
	ds_read_b128 v[50:53], v38 offset:42848
	ds_read_b128 v[46:49], v38 offset:42592
	ds_read_b32 v62, v39 offset:43616
	ds_read_b128 v[42:45], v38 offset:42336
	ds_read_b128 v[54:57], v38 offset:43104
	ds_read_b128 v[58:61], v38 offset:43360
	v_pk_mul_f32 v[34:35], v[22:23], v[10:11]
	v_pk_fma_f32 v[34:35], v[24:25], v[12:13], v[34:35]
	v_add_f32_e32 v34, v34, v35
	v_add_f32_e32 v66, v66, v67
	v_pk_mul_f32 v[6:7], v[6:7], v[28:29] op_sel_hi:[1,0]
	v_add_f32_dpp v34, v34, v34 row_ror:1 row_mask:0xf bank_mask:0xf bound_ctrl:1
	v_add_f32_dpp v66, v66, v66 row_ror:1 row_mask:0xf bank_mask:0xf bound_ctrl:1
	s_waitcnt lgkmcnt(7)
	v_pk_fma_f32 v[6:7], v[22:23], v[2:3], v[6:7]
	v_add_f32_dpp v34, v34, v34 row_ror:2 row_mask:0xf bank_mask:0xf bound_ctrl:1
	v_add_f32_dpp v66, v66, v66 row_ror:2 row_mask:0xf bank_mask:0xf bound_ctrl:1
	v_pk_mul_f32 v[8:9], v[8:9], v[28:29] op_sel_hi:[1,0]
	v_add_f32_dpp v34, v34, v34 row_ror:4 row_mask:0xf bank_mask:0xf bound_ctrl:1
	v_pk_fma_f32 v[8:9], v[24:25], v[4:5], v[8:9]
	ds_write2st64_b32 v41, v36, v66 offset0:24 offset1:25
	v_add_f32_dpp v34, v34, v34 row_ror:8 row_mask:0xf bank_mask:0xf bound_ctrl:1
	v_pk_fma_f32 v[22:23], v[14:15], v[34:35], v[6:7] op_sel_hi:[1,0,1]
	v_pk_fma_f32 v[24:25], v[16:17], v[34:35], v[8:9] op_sel_hi:[1,0,1]
	s_waitcnt lgkmcnt(4)
	v_pk_mul_f32 v[36:37], v[22:23], v[18:19]
	v_pk_fma_f32 v[36:37], v[24:25], v[20:21], v[36:37]
	ds_read_b128 v[10:13], v38 offset:44416
	ds_read_b128 v[6:9], v38 offset:44160
	ds_read_b32 v28, v39 offset:45184
	ds_read_b128 v[2:5], v38 offset:43904
	ds_read_b128 v[14:17], v38 offset:44672
	ds_read_b128 v[18:21], v38 offset:44928
	v_pk_mul_f32 v[34:35], v[22:23], v[50:51]
	v_pk_fma_f32 v[34:35], v[24:25], v[52:53], v[34:35]
	v_add_f32_e32 v34, v34, v35
	v_add_f32_e32 v36, v36, v37
	v_pk_mul_f32 v[46:47], v[46:47], v[62:63] op_sel_hi:[1,0]
	v_add_f32_dpp v34, v34, v34 row_ror:1 row_mask:0xf bank_mask:0xf bound_ctrl:1
	v_add_f32_dpp v36, v36, v36 row_ror:1 row_mask:0xf bank_mask:0xf bound_ctrl:1
	s_waitcnt lgkmcnt(8)
	v_pk_fma_f32 v[46:47], v[22:23], v[42:43], v[46:47]
	v_add_f32_dpp v34, v34, v34 row_ror:2 row_mask:0xf bank_mask:0xf bound_ctrl:1
	v_add_f32_dpp v36, v36, v36 row_ror:2 row_mask:0xf bank_mask:0xf bound_ctrl:1
	v_pk_mul_f32 v[48:49], v[48:49], v[62:63] op_sel_hi:[1,0]
	v_add_f32_dpp v34, v34, v34 row_ror:4 row_mask:0xf bank_mask:0xf bound_ctrl:1
	v_pk_fma_f32 v[48:49], v[24:25], v[44:45], v[48:49]
	s_nop 0
	v_add_f32_dpp v34, v34, v34 row_ror:8 row_mask:0xf bank_mask:0xf bound_ctrl:1
	v_pk_fma_f32 v[22:23], v[54:55], v[34:35], v[46:47] op_sel_hi:[1,0,1]
	v_pk_fma_f32 v[24:25], v[56:57], v[34:35], v[48:49] op_sel_hi:[1,0,1]
	s_waitcnt lgkmcnt(3)
; template <int CTRL> __device__ __forceinline__ float dpp_f(float x) { return __int_as_float(__builtin_amdgcn_update_dpp(0, __float_as_int(x), CTRL, 0xf, 0xf, false)); }
; __device__ __forceinline__ void p8_scan(const Args& a, LAS unsigned char* lds) {
;     ...
;                 for (int tt = 0; tt < TC; ++tt) {
;                     ScanOps n; scan_ld(n, bt + (tt + 1 < TC ? tt + 1 : tt) * SPITCH, jq4, myrow);
;                     __builtin_amdgcn_sched_barrier(0);
;                     f32x2 ta = S01 * o.al.lo, ty = S01 * o.wr.lo; ta = S23 * o.al.hi + ta; ty = S23 * o.wr.hi + ty;
;                     float pa = ta.x + ta.y, py = ty.x + ty.y;
;                     f32x2 kv01 = o.kv.lo * o.vi, kv23 = o.kv.hi * o.vi;
;     ...
;                     asm volatile("" : "+v"(kv01), "+v"(kv23), "+v"(vc));
;                     pa += dpp_f<0x121>(pa); py += dpp_f<0x121>(py); pa += dpp_f<0x122>(pa); py += dpp_f<0x122>(py);
;                     pa += dpp_f<0x124>(pa); pa += dpp_f<0x128>(pa);
;                     S01 = S01 * o.wv.lo + (o.be.lo * pa + kv01);
;                     S23 = S23 * o.wv.hi + (o.be.hi * pa + kv23);
;     ...
;                     __builtin_amdgcn_sched_barrier(0);
;                     o = n;
;                 }
;                 __syncthreads();
;             }
	v_pk_mul_f32 v[66:67], v[22:23], v[58:59]
	v_pk_fma_f32 v[66:67], v[24:25], v[60:61], v[66:67]
	ds_read_b128 v[50:53], v38 offset:45984
	ds_read_b128 v[46:49], v38 offset:45728
	ds_read_b32 v62, v39 offset:46752
	ds_read_b128 v[42:45], v38 offset:45472
	ds_read_b128 v[54:57], v38 offset:46240
	ds_read_b128 v[58:61], v38 offset:46496
	v_pk_mul_f32 v[34:35], v[22:23], v[10:11]
	v_pk_fma_f32 v[34:35], v[24:25], v[12:13], v[34:35]
	v_add_f32_e32 v34, v34, v35
	v_add_f32_e32 v66, v66, v67
	v_pk_mul_f32 v[6:7], v[6:7], v[28:29] op_sel_hi:[1,0]
	v_add_f32_dpp v34, v34, v34 row_ror:1 row_mask:0xf bank_mask:0xf bound_ctrl:1
	v_add_f32_dpp v66, v66, v66 row_ror:1 row_mask:0xf bank_mask:0xf bound_ctrl:1
	s_waitcnt lgkmcnt(7)
	v_pk_fma_f32 v[6:7], v[22:23], v[2:3], v[6:7]
	v_add_f32_dpp v34, v34, v34 row_ror:2 row_mask:0xf bank_mask:0xf bound_ctrl:1
	v_add_f32_dpp v66, v66, v66 row_ror:2 row_mask:0xf bank_mask:0xf bound_ctrl:1
	v_pk_mul_f32 v[8:9], v[8:9], v[28:29] op_sel_hi:[1,0]
	v_add_f32_dpp v34, v34, v34 row_ror:4 row_mask:0xf bank_mask:0xf bound_ctrl:1
	v_pk_fma_f32 v[8:9], v[24:25], v[4:5], v[8:9]
	ds_write2st64_b32 v41, v36, v66 offset0:26 offset1:27
	v_add_f32_dpp v34, v34, v34 row_ror:8 row_mask:0xf bank_mask:0xf bound_ctrl:1
	v_pk_fma_f32 v[22:23], v[14:15], v[34:35], v[6:7] op_sel_hi:[1,0,1]
	v_pk_fma_f32 v[24:25], v[16:17], v[34:35], v[8:9] op_sel_hi:[1,0,1]
	s_waitcnt lgkmcnt(4)
	v_pk_mul_f32 v[36:37], v[22:23], v[18:19]
	v_pk_fma_f32 v[36:37], v[24:25], v[20:21], v[36:37]
	ds_read_b128 v[10:13], v38 offset:47552
	ds_read_b128 v[6:9], v38 offset:47296
	ds_read_b32 v28, v39 offset:48320
	ds_read_b128 v[2:5], v38 offset:47040
	ds_read_b128 v[14:17], v38 offset:47808
	ds_read_b128 v[18:21], v38 offset:48064
	v_pk_mul_f32 v[34:35], v[22:23], v[50:51]
	v_pk_fma_f32 v[34:35], v[24:25], v[52:53], v[34:35]
	v_add_f32_e32 v34, v34, v35
	v_add_f32_e32 v36, v36, v37
	v_pk_mul_f32 v[46:47], v[46:47], v[62:63] op_sel_hi:[1,0]
	v_add_f32_dpp v34, v34, v34 row_ror:1 row_mask:0xf bank_mask:0xf bound_ctrl:1
	v_add_f32_dpp v36, v36, v36 row_ror:1 row_mask:0xf bank_mask:0xf bound_ctrl:1
	s_waitcnt lgkmcnt(8)
	v_pk_fma_f32 v[46:47], v[22:23], v[42:43], v[46:47]
	v_add_f32_dpp v34, v34, v34 row_ror:2 row_mask:0xf bank_mask:0xf bound_ctrl:1
	v_add_f32_dpp v36, v36, v36 row_ror:2 row_mask:0xf bank_mask:0xf bound_ctrl:1
	v_pk_mul_f32 v[48:49], v[48:49], v[62:63] op_sel_hi:[1,0]
	v_add_f32_dpp v34, v34, v34 row_ror:4 row_mask:0xf bank_mask:0xf bound_ctrl:1
	v_pk_fma_f32 v[48:49], v[24:25], v[44:45], v[48:49]
	s_nop 0
	v_add_f32_dpp v34, v34, v34 row_ror:8 row_mask:0xf bank_mask:0xf bound_ctrl:1
	v_pk_fma_f32 v[22:23], v[54:55], v[34:35], v[46:47] op_sel_hi:[1,0,1]
	v_pk_fma_f32 v[24:25], v[56:57], v[34:35], v[48:49] op_sel_hi:[1,0,1]
	s_waitcnt lgkmcnt(3)
	v_pk_mul_f32 v[66:67], v[22:23], v[58:59]
	v_pk_fma_f32 v[66:67], v[24:25], v[60:61], v[66:67]
	ds_read_b128 v[50:53], v38 offset:49120
	ds_read_b128 v[46:49], v38 offset:48864
	ds_read_b32 v62, v39 offset:49888
	ds_read_b128 v[42:45], v38 offset:48608
	ds_read_b128 v[54:57], v38 offset:49376
	ds_read_b128 v[58:61], v38 offset:49632
	v_pk_mul_f32 v[34:35], v[22:23], v[10:11]
	v_pk_fma_f32 v[34:35], v[24:25], v[12:13], v[34:35]
	v_add_f32_e32 v34, v34, v35
	v_add_f32_e32 v66, v66, v67
	v_pk_mul_f32 v[6:7], v[6:7], v[28:29] op_sel_hi:[1,0]
	v_add_f32_dpp v34, v34, v34 row_ror:1 row_mask:0xf bank_mask:0xf bound_ctrl:1
	v_add_f32_dpp v66, v66, v66 row_ror:1 row_mask:0xf bank_mask:0xf bound_ctrl:1
	s_waitcnt lgkmcnt(7)
	v_pk_fma_f32 v[6:7], v[22:23], v[2:3], v[6:7]
	v_add_f32_dpp v34, v34, v34 row_ror:2 row_mask:0xf bank_mask:0xf bound_ctrl:1
	v_add_f32_dpp v66, v66, v66 row_ror:2 row_mask:0xf bank_mask:0xf bound_ctrl:1
	v_pk_mul_f32 v[8:9], v[8:9], v[28:29] op_sel_hi:[1,0]
	v_add_f32_dpp v34, v34, v34 row_ror:4 row_mask:0xf bank_mask:0xf bound_ctrl:1
	v_pk_fma_f32 v[8:9], v[24:25], v[4:5], v[8:9]
	ds_write2st64_b32 v41, v36, v66 offset0:28 offset1:29
	v_add_f32_dpp v34, v34, v34 row_ror:8 row_mask:0xf bank_mask:0xf bound_ctrl:1
	v_pk_fma_f32 v[22:23], v[14:15], v[34:35], v[6:7] op_sel_hi:[1,0,1]
	v_pk_fma_f32 v[24:25], v[16:17], v[34:35], v[8:9] op_sel_hi:[1,0,1]
	s_waitcnt lgkmcnt(4)
	v_pk_mul_f32 v[36:37], v[22:23], v[18:19]
	v_pk_fma_f32 v[36:37], v[24:25], v[20:21], v[36:37]
	v_pk_mul_f32 v[34:35], v[22:23], v[50:51]
	v_pk_fma_f32 v[34:35], v[24:25], v[52:53], v[34:35]
	v_add_f32_e32 v34, v34, v35
	v_add_f32_e32 v36, v36, v37
	v_pk_mul_f32 v[46:47], v[46:47], v[62:63] op_sel_hi:[1,0]
	v_add_f32_dpp v34, v34, v34 row_ror:1 row_mask:0xf bank_mask:0xf bound_ctrl:1
	v_add_f32_dpp v36, v36, v36 row_ror:1 row_mask:0xf bank_mask:0xf bound_ctrl:1
	s_waitcnt lgkmcnt(1)
	v_pk_fma_f32 v[46:47], v[22:23], v[42:43], v[46:47]
	v_add_f32_dpp v34, v34, v34 row_ror:2 row_mask:0xf bank_mask:0xf bound_ctrl:1
	v_add_f32_dpp v36, v36, v36 row_ror:2 row_mask:0xf bank_mask:0xf bound_ctrl:1
	v_pk_mul_f32 v[48:49], v[48:49], v[62:63] op_sel_hi:[1,0]
	v_add_f32_dpp v34, v34, v34 row_ror:4 row_mask:0xf bank_mask:0xf bound_ctrl:1
	v_pk_fma_f32 v[48:49], v[24:25], v[44:45], v[48:49]
	s_nop 0
	v_add_f32_dpp v34, v34, v34 row_ror:8 row_mask:0xf bank_mask:0xf bound_ctrl:1
	v_pk_fma_f32 v[22:23], v[54:55], v[34:35], v[46:47] op_sel_hi:[1,0,1]
	v_pk_fma_f32 v[24:25], v[56:57], v[34:35], v[48:49] op_sel_hi:[1,0,1]
	v_pk_mul_f32 v[66:67], v[22:23], v[58:59]
	v_pk_fma_f32 v[66:67], v[24:25], v[60:61], v[66:67]
	v_add_f32_e32 v66, v66, v67
	s_nop 1
	v_add_f32_dpp v66, v66, v66 row_ror:1 row_mask:0xf bank_mask:0xf bound_ctrl:1
	s_nop 1
	v_add_f32_dpp v66, v66, v66 row_ror:2 row_mask:0xf bank_mask:0xf bound_ctrl:1
	ds_write2st64_b32 v41, v36, v66 offset0:30 offset1:31
	s_add_i32 s14, s14, 1
	s_cmpk_eq_i32 s14, 0x100
	s_waitcnt lgkmcnt(0)
	s_barrier
	s_cbranch_scc0 .LBB0_1090
	s_setprio 0
	s_mov_b64 s[44:45], 0

; __device__ __forceinline__ void scan_issue(ScanRegs& R, const bf16_t* PRKV, const unsigned short* WLOG, const bf16_t* ASIG, size_t tok, int ch, int want_prev) {
; __device__ __forceinline__ float scan_prepare(const ScanRegs& R, const u32x2 qr_, const u32x2 qk_, const u32x2 qv_, LAS float* slot, int cq, const f32x4 mur, const f32x4 muk, const f32x4 muv, const f32x4 kkc, const f32x4 kac, const f32x4 rkc) {
;     float pr[4], pk[4], pv[4], qr[4], qk[4], qv[4], av[4], om[4];
;     unpack4(R.pr, pr); unpack4(R.pk, pk); unpack4(R.pv, pv); unpack4(qr_, qr); unpack4(qk_, qk); unpack4(qv_, qv); unpack4(R.as, av);
;     om[0] = f16_to_f((unsigned short)(R.wl.x & 0xffffu)); om[1] = f16_to_f((unsigned short)(R.wl.x >> 16)); om[2] = f16_to_f((unsigned short)(R.wl.y & 0xffffu)); om[3] = f16_to_f((unsigned short)(R.wl.y >> 16));
;     float rr[4], vv[4], kn[4], k2[4], dec[4], bu[4];
;     float ssq = 0.f, bon = 0.f, c1 = 0.f, c2 = 0.f;
; #pragma unroll
;     for (int j = 0; j < 4; ++j) {
;         rr[j] = pr[j] + (qr[j] - pr[j]) * mur[j]; const float kk0 = pk[j] + (qk[j] - pk[j]) * muk[j]; vv[j] = pv[j] + (qv[j] - pv[j]) * muv[j];
;         dec[j] = 1.0f - om[j];
;         kn[j] = kk0 * kkc[j]; ssq += kn[j] * kn[j];
;         k2[j] = kk0 * (1.0f + (av[j] - 1.0f) * kac[j]);
;         const float t = rr[j] * k2[j]; bon += t * rkc[j]; c2 += t;
;         bu[j] = kn[j] * av[j]; c1 += bu[j] * rr[j];
;     }
;     ssq += dpp_f<0x121>(ssq); bon += dpp_f<0x121>(bon); c1 += dpp_f<0x121>(c1); c2 += dpp_f<0x121>(c2);
;     ssq += dpp_f<0x122>(ssq); bon += dpp_f<0x122>(bon); c1 += dpp_f<0x122>(c1); c2 += dpp_f<0x122>(c2);
;     ssq += dpp_f<0x124>(ssq); bon += dpp_f<0x124>(bon); c1 += dpp_f<0x124>(c1); c2 += dpp_f<0x124>(c2);
;     ssq += dpp_f<0x128>(ssq); bon += dpp_f<0x128>(bon); c1 += dpp_f<0x128>(c1); c2 += dpp_f<0x128>(c2);
;     const float inv = __builtin_amdgcn_rsqf(fmaxf(ssq, 1e-24f));
;     f32x4 o_al, o_be, o_wr;
; #pragma unroll
;     for (int j = 0; j < 4; ++j) { o_al[j] = -(kn[j] * inv); o_be[j] = bu[j] * inv; o_wr[j] = dec[j] * rr[j]; }
;     LAS f32x4* s4 = (LAS f32x4*)slot;
;     s4[cq] = (f32x4){dec[0], dec[1], dec[2], dec[3]}; s4[16 + cq] = (f32x4){k2[0], k2[1], k2[2], k2[3]}; s4[32 + cq] = o_al; s4[48 + cq] = o_be; s4[64 + cq] = o_wr;
;     s4[80 + cq] = (f32x4){vv[0], vv[1], vv[2], vv[3]};
;     if (cq == 0) *(LAS f32x2*)(slot + 384) = (f32x2){c1 * inv, c2};
.LBB0_1097:
	s_or_b64 exec, exec, s[44:45]
	v_lshlrev_b32_e32 v32, 11, v139
	v_mov_b32_e32 v33, v29
	v_lshl_add_u64 v[42:43], s[90:91], 0, v[32:33]
	v_lshl_add_u64 v[42:43], v[42:43], 0, v[28:29]
	global_load_dwordx2 v[60:61], v[42:43], off
	v_lshl_add_u64 v[36:37], s[8:9], 0, v[32:33]
	v_lshl_add_u64 v[36:37], v[36:37], 0, v[28:29]
	s_mov_b64 s[44:45], 0x1800
	global_load_dwordx2 v[62:63], v[36:37], off
	v_or_b32_e32 v1, 1, v139
	s_waitcnt vmcnt(3)
	v_lshlrev_b32_e32 v46, 16, v38
	v_and_b32_e32 v47, 0xffff0000, v38
	s_waitcnt vmcnt(2)
	v_lshlrev_b32_e32 v36, 16, v52
	v_and_b32_e32 v37, 0xffff0000, v52
	v_lshlrev_b32_e32 v44, 16, v39
	v_and_b32_e32 v45, 0xffff0000, v39
	v_lshlrev_b32_e32 v38, 16, v53
	v_and_b32_e32 v39, 0xffff0000, v53
	v_lshlrev_b32_e32 v52, 16, v55
	v_and_b32_e32 v53, 0xffff0000, v55
	v_lshl_add_u64 v[34:35], v[34:35], 0, s[44:45]
	v_mov_b32_e32 v57, v29
	v_lshlrev_b32_e32 v58, 16, v54
	v_and_b32_e32 v59, 0xffff0000, v54
	v_lshlrev_b32_e32 v54, 16, v50
	v_and_b32_e32 v55, 0xffff0000, v50
	v_lshlrev_b32_e32 v50, 16, v51
	v_and_b32_e32 v51, 0xffff0000, v51
	s_movk_i32 s43, 0x1000
	v_lshlrev_b32_e32 v56, 11, v1
	v_pk_add_f32 v[52:53], v[52:53], v[38:39] neg_lo:[0,1] neg_hi:[0,1]
	v_lshl_add_u64 v[72:73], v[34:35], 0, v[28:29]
	v_lshlrev_b32_e32 v42, 16, v40
	v_and_b32_e32 v43, 0xffff0000, v40
	v_lshlrev_b32_e32 v64, 16, v48
	v_and_b32_e32 v65, 0xffff0000, v48
	v_pk_add_f32 v[70:71], v[50:51], v[44:45] neg_lo:[0,1] neg_hi:[0,1]
	v_lshl_add_u64 v[50:51], s[8:9], 0, v[56:57]
	v_lshl_add_u64 v[56:57], s[90:91], 0, v[56:57]
	v_pk_fma_f32 v[66:67], v[8:9], v[52:53], v[38:39]
	v_add_co_u32_e32 v52, vcc, s43, v72
	v_pk_add_f32 v[58:59], v[58:59], v[36:37] neg_lo:[0,1] neg_hi:[0,1]
	v_pk_add_f32 v[54:55], v[54:55], v[46:47] neg_lo:[0,1] neg_hi:[0,1]
	v_pk_add_f32 v[68:69], v[64:65], v[42:43] neg_lo:[0,1] neg_hi:[0,1]
	v_addc_co_u32_e32 v53, vcc, 0, v73, vcc
	v_lshl_add_u64 v[56:57], v[56:57], 0, v[28:29]
	v_pk_fma_f32 v[64:65], v[6:7], v[58:59], v[36:37]
	v_pk_fma_f32 v[74:75], v[2:3], v[54:55], v[46:47]
	v_pk_fma_f32 v[84:85], v[10:11], v[68:69], v[42:43]
	v_lshl_add_u64 v[68:69], v[50:51], 0, v[28:29]
	global_load_dwordx2 v[50:51], v[72:73], off
	global_load_dwordx2 v[54:55], v[72:73], off offset:2048
	global_load_dwordx2 v[58:59], v[52:53], off
	s_nop 0
	global_load_dwordx2 v[52:53], v[68:69], off
	s_nop 0
	global_load_dwordx2 v[56:57], v[56:57], off
	v_pk_fma_f32 v[70:71], v[4:5], v[70:71], v[44:45]
	v_pk_mul_f32 v[76:77], v[14:15], v[74:75]
	v_pk_mul_f32 v[78:79], v[16:17], v[70:71]
	v_pk_mul_f32 v[68:69], v[76:77], v[76:77]
	v_pk_mul_f32 v[72:73], v[78:79], v[78:79]
	v_add_f32_e32 v33, v68, v69
	v_add_f32_e32 v33, v72, v33
	v_add_f32_e32 v33, v73, v33
	v_lshlrev_b32_e32 v40, 16, v41
	v_and_b32_e32 v41, 0xffff0000, v41
	v_add_f32_dpp v33, v33, v33 row_ror:1 row_mask:0xf bank_mask:0xf bound_ctrl:1
	s_waitcnt vmcnt(6)
	v_lshlrev_b32_e32 v68, 16, v60
	v_and_b32_e32 v69, 0xffff0000, v60
	v_pk_add_f32 v[80:81], v[68:69], -1.0 op_sel_hi:[1,0]
	v_add_f32_dpp v33, v33, v33 row_ror:2 row_mask:0xf bank_mask:0xf bound_ctrl:1
	v_pk_mul_f32 v[86:87], v[76:77], v[68:69]
	v_pk_fma_f32 v[68:69], v[18:19], v[80:81], 1.0 op_sel_hi:[1,1,0]
	v_add_f32_dpp v33, v33, v33 row_ror:4 row_mask:0xf bank_mask:0xf bound_ctrl:1
	v_pk_mul_f32 v[80:81], v[84:85], v[86:87]
	v_pk_mul_f32 v[68:69], v[74:75], v[68:69]
	v_add_f32_dpp v33, v33, v33 row_ror:8 row_mask:0xf bank_mask:0xf bound_ctrl:1
	v_add_f32_e32 v48, 0, v80
	v_pk_mul_f32 v[74:75], v[84:85], v[68:69]
	v_max_f32_e32 v33, 0x179abe15, v33
	v_lshlrev_b32_e32 v60, 16, v61
	v_and_b32_e32 v61, 0xffff0000, v61
	v_add_f32_e32 v90, v81, v48
	v_add_f32_e32 v48, 0, v74
	v_pk_add_f32 v[82:83], v[60:61], -1.0 op_sel_hi:[1,0]
	v_fma_f32 v91, v22, v74, 0
	v_add_f32_e32 v92, v75, v48
	v_rsq_f32_e32 v48, v33
	v_fmac_f32_e32 v91, v23, v75
	v_pk_fma_f32 v[74:75], v[20:21], v[82:83], 1.0 op_sel_hi:[1,1,0]
	v_pk_mul_f32 v[60:61], v[78:79], v[60:61]
	v_pk_mul_f32 v[70:71], v[70:71], v[74:75]
	v_lshlrev_b32_e32 v74, 16, v49
	v_and_b32_e32 v75, 0xffff0000, v49
	v_pk_add_f32 v[74:75], v[74:75], v[40:41] neg_lo:[0,1] neg_hi:[0,1]
	v_pk_mul_f32 v[80:81], v[86:87], v[48:49] op_sel_hi:[1,0]
	v_pk_fma_f32 v[86:87], v[12:13], v[74:75], v[40:41]
	s_waitcnt vmcnt(5)
	v_cvt_f32_f16_e32 v72, v62
	v_cvt_f32_f16_sdwa v73, v62 dst_sel:DWORD dst_unused:UNUSED_PAD src0_sel:WORD_1
	v_pk_mul_f32 v[82:83], v[60:61], v[48:49] op_sel_hi:[1,0]
	v_cvt_f32_f16_e32 v62, v63
	v_cvt_f32_f16_sdwa v63, v63 dst_sel:DWORD dst_unused:UNUSED_PAD src0_sel:WORD_1
	v_pk_mul_f32 v[88:89], v[86:87], v[70:71]
	v_pk_mul_f32 v[60:61], v[86:87], v[60:61]
	v_pk_mul_f32 v[78:79], v[78:79], v[48:49] op_sel_hi:[1,0] neg_lo:[0,1] neg_hi:[0,1]
	v_pk_mul_f32 v[76:77], v[76:77], v[48:49] op_sel_hi:[1,0] neg_lo:[0,1] neg_hi:[0,1]
	v_fmac_f32_e32 v91, v24, v88
	v_add_f32_e32 v33, v88, v92
	v_add_f32_e32 v49, v60, v90
	v_fmac_f32_e32 v91, v25, v89
	v_add_f32_e32 v33, v89, v33
	v_add_f32_e32 v49, v61, v49
	v_add_f32_dpp v60, v91, v91 row_ror:1 row_mask:0xf bank_mask:0xf bound_ctrl:1
	v_add_f32_dpp v33, v33, v33 row_ror:1 row_mask:0xf bank_mask:0xf bound_ctrl:1
	v_add_f32_dpp v49, v49, v49 row_ror:1 row_mask:0xf bank_mask:0xf bound_ctrl:1
	v_pk_add_f32 v[74:75], v[62:63], 1.0 op_sel_hi:[1,0] neg_lo:[1,0] neg_hi:[1,0]
	v_add_f32_dpp v60, v60, v60 row_ror:2 row_mask:0xf bank_mask:0xf bound_ctrl:1
	v_add_f32_dpp v49, v49, v49 row_ror:2 row_mask:0xf bank_mask:0xf bound_ctrl:1
	v_add_f32_dpp v62, v33, v33 row_ror:2 row_mask:0xf bank_mask:0xf bound_ctrl:1
	v_add_f32_dpp v33, v60, v60 row_ror:4 row_mask:0xf bank_mask:0xf bound_ctrl:1
	v_add_f32_dpp v61, v49, v49 row_ror:4 row_mask:0xf bank_mask:0xf bound_ctrl:1
	v_add_f32_dpp v60, v62, v62 row_ror:4 row_mask:0xf bank_mask:0xf bound_ctrl:1
	v_mov_b32_e32 v62, v29
	v_mov_b32_e32 v63, v29
	v_mov_b32_e32 v49, v29
	v_pk_add_f32 v[72:73], v[72:73], 1.0 op_sel_hi:[1,0] neg_lo:[1,0] neg_hi:[1,0]
	v_mov_b32_dpp v62, v61 row_ror:8 row_mask:0xf bank_mask:0xf
	v_mov_b32_dpp v63, v60 row_ror:8 row_mask:0xf bank_mask:0xf
	v_mov_b32_dpp v49, v33 row_ror:8 row_mask:0xf bank_mask:0xf
	v_pk_mul_f32 v[84:85], v[84:85], 1.0 op_sel_hi:[1,0]
	v_pk_mul_f32 v[86:87], v[86:87], 1.0 op_sel_hi:[1,0]
	ds_write_b128 v127, v[72:75]
	ds_write_b128 v127, v[68:71] offset:256
	ds_write_b128 v127, v[76:79] offset:512
	ds_write_b128 v127, v[80:83] offset:768
	ds_write_b128 v127, v[84:87] offset:1024
	ds_write_b128 v127, v[64:67] offset:1280
	s_and_saveexec_b64 s[44:45], s[4:5]
	v_add_f32_e32 v61, v61, v62
	v_mul_f32_e32 v62, v61, v48
	v_add_f32_e32 v63, v60, v63
	ds_write_b64 v126, v[62:63] offset:1536
	s_or_b64 exec, exec, s[44:45]
	s_waitcnt vmcnt(2)
; #define LAS __attribute__((address_space(3)))
; __device__ __forceinline__ float f16_to_f(unsigned short h) { return (float)__builtin_bit_cast(_Float16, h); }
; __device__ __forceinline__ float scan_prepare(const ScanRegs& R, const u32x2 qr_, const u32x2 qk_, const u32x2 qv_, LAS float* slot, int cq, const f32x4 mur, const f32x4 muk, const f32x4 muv, const f32x4 kkc, const f32x4 kac, const f32x4 rkc) {
;     float pr[4], pk[4], pv[4], qr[4], qk[4], qv[4], av[4], om[4];
;     unpack4(R.pr, pr); unpack4(R.pk, pk); unpack4(R.pv, pv); unpack4(qr_, qr); unpack4(qk_, qk); unpack4(qv_, qv); unpack4(R.as, av);
;     om[0] = f16_to_f((unsigned short)(R.wl.x & 0xffffu)); om[1] = f16_to_f((unsigned short)(R.wl.x >> 16)); om[2] = f16_to_f((unsigned short)(R.wl.y & 0xffffu)); om[3] = f16_to_f((unsigned short)(R.wl.y >> 16));
;     float rr[4], vv[4], kn[4], k2[4], dec[4], bu[4];
;     float ssq = 0.f, bon = 0.f, c1 = 0.f, c2 = 0.f;
; #pragma unroll
;     for (int j = 0; j < 4; ++j) {
;         rr[j] = pr[j] + (qr[j] - pr[j]) * mur[j]; const float kk0 = pk[j] + (qk[j] - pk[j]) * muk[j]; vv[j] = pv[j] + (qv[j] - pv[j]) * muv[j];
;         dec[j] = 1.0f - om[j];
;         kn[j] = kk0 * kkc[j]; ssq += kn[j] * kn[j];
;         k2[j] = kk0 * (1.0f + (av[j] - 1.0f) * kac[j]);
;         const float t = rr[j] * k2[j]; bon += t * rkc[j]; c2 += t;
;         bu[j] = kn[j] * av[j]; c1 += bu[j] * rr[j];
;     }
;     ssq += dpp_f<0x121>(ssq); bon += dpp_f<0x121>(bon); c1 += dpp_f<0x121>(c1); c2 += dpp_f<0x121>(c2);
;     ssq += dpp_f<0x122>(ssq); bon += dpp_f<0x122>(bon); c1 += dpp_f<0x122>(c1); c2 += dpp_f<0x122>(c2);
;     ssq += dpp_f<0x124>(ssq); bon += dpp_f<0x124>(bon); c1 += dpp_f<0x124>(c1); c2 += dpp_f<0x124>(c2);
;     ssq += dpp_f<0x128>(ssq); bon += dpp_f<0x128>(bon); c1 += dpp_f<0x128>(c1); c2 += dpp_f<0x128>(c2);
;     const float inv = __builtin_amdgcn_rsqf(fmaxf(ssq, 1e-24f));
;     f32x4 o_al, o_be, o_wr;
; #pragma unroll
;     for (int j = 0; j < 4; ++j) { o_al[j] = -(kn[j] * inv); o_be[j] = bu[j] * inv; o_wr[j] = dec[j] * rr[j]; }
;     LAS f32x4* s4 = (LAS f32x4*)slot;
;     s4[cq] = (f32x4){dec[0], dec[1], dec[2], dec[3]}; s4[16 + cq] = (f32x4){k2[0], k2[1], k2[2], k2[3]}; s4[32 + cq] = o_al; s4[48 + cq] = o_be; s4[64 + cq] = o_wr;
;     s4[80 + cq] = (f32x4){vv[0], vv[1], vv[2], vv[3]};
;     if (cq == 0) *(LAS f32x2*)(slot + 384) = (f32x2){c1 * inv, c2};
	v_lshlrev_b32_e32 v70, 16, v58
	v_and_b32_e32 v71, 0xffff0000, v58
	v_lshlrev_b32_e32 v72, 16, v59
	v_and_b32_e32 v73, 0xffff0000, v59
	v_lshlrev_b32_e32 v58, 16, v54
	v_and_b32_e32 v59, 0xffff0000, v54
	v_pk_add_f32 v[46:47], v[46:47], v[58:59] neg_lo:[0,1] neg_hi:[0,1]
	s_waitcnt vmcnt(0)
	v_lshlrev_b32_e32 v60, 16, v56
	v_pk_fma_f32 v[46:47], v[2:3], v[46:47], v[58:59]
	v_and_b32_e32 v61, 0xffff0000, v56
	v_pk_mul_f32 v[64:65], v[14:15], v[46:47]
	v_pk_add_f32 v[58:59], v[60:61], -1.0 op_sel_hi:[1,0]
	v_pk_mul_f32 v[74:75], v[64:65], v[60:61]
	v_lshlrev_b32_e32 v60, 16, v50
	v_and_b32_e32 v61, 0xffff0000, v50
	v_pk_fma_f32 v[58:59], v[18:19], v[58:59], 1.0 op_sel_hi:[1,1,0]
	v_pk_add_f32 v[42:43], v[42:43], v[60:61] neg_lo:[0,1] neg_hi:[0,1]
	v_pk_mul_f32 v[58:59], v[46:47], v[58:59]
	v_pk_fma_f32 v[76:77], v[10:11], v[42:43], v[60:61]
	v_pk_mul_f32 v[66:67], v[64:65], v[64:65]
	v_pk_mul_f32 v[42:43], v[76:77], v[58:59]
	v_cvt_f32_f16_sdwa v47, v52 dst_sel:DWORD dst_unused:UNUSED_PAD src0_sel:WORD_1
	v_fma_f32 v48, v22, v42, 0
	v_add_f32_e32 v42, 0, v42
	v_fmac_f32_e32 v48, v23, v43
	v_add_f32_e32 v78, v43, v42
	v_lshlrev_b32_e32 v42, 16, v55
	v_and_b32_e32 v43, 0xffff0000, v55
	v_pk_add_f32 v[44:45], v[44:45], v[42:43] neg_lo:[0,1] neg_hi:[0,1]
	v_cvt_f32_f16_e32 v46, v52
	v_pk_fma_f32 v[44:45], v[4:5], v[44:45], v[42:43]
	v_add_f32_e32 v50, v66, v67
	v_pk_mul_f32 v[54:55], v[16:17], v[44:45]
	v_pk_add_f32 v[62:63], v[46:47], 1.0 op_sel_hi:[1,0] neg_lo:[1,0] neg_hi:[1,0]
	v_pk_mul_f32 v[42:43], v[54:55], v[54:55]
	v_pk_mul_f32 v[46:47], v[76:77], v[74:75]
	v_add_f32_e32 v42, v42, v50
	v_add_f32_e32 v42, v43, v42
	v_add_f32_e32 v46, 0, v46
	v_add_f32_e32 v79, v47, v46
	v_add_f32_dpp v42, v42, v42 row_ror:1 row_mask:0xf bank_mask:0xf bound_ctrl:1
	v_lshlrev_b32_e32 v46, 16, v57
	v_and_b32_e32 v47, 0xffff0000, v57
	v_add_f32_dpp v42, v42, v42 row_ror:2 row_mask:0xf bank_mask:0xf bound_ctrl:1
	v_pk_add_f32 v[56:57], v[46:47], -1.0 op_sel_hi:[1,0]
	v_cvt_f32_f16_e32 v50, v53
	v_add_f32_dpp v42, v42, v42 row_ror:4 row_mask:0xf bank_mask:0xf bound_ctrl:1
	v_pk_fma_f32 v[56:57], v[20:21], v[56:57], 1.0 op_sel_hi:[1,1,0]
	v_pk_add_f32 v[36:37], v[36:37], v[70:71] neg_lo:[0,1] neg_hi:[0,1]
	v_add_f32_dpp v42, v42, v42 row_ror:8 row_mask:0xf bank_mask:0xf bound_ctrl:1
	v_max_f32_e32 v42, 0x179abe15, v42
	v_rsq_f32_e32 v42, v42
	v_pk_mul_f32 v[60:61], v[44:45], v[56:57]
	v_pk_mul_f32 v[44:45], v[54:55], v[46:47]
	v_lshlrev_b32_e32 v46, 16, v51
	v_and_b32_e32 v47, 0xffff0000, v51
	v_pk_add_f32 v[40:41], v[40:41], v[46:47] neg_lo:[0,1] neg_hi:[0,1]
	v_cvt_f32_f16_sdwa v51, v53 dst_sel:DWORD dst_unused:UNUSED_PAD src0_sel:WORD_1
	v_pk_fma_f32 v[52:53], v[12:13], v[40:41], v[46:47]
	v_pk_mul_f32 v[68:69], v[44:45], v[42:43] op_sel_hi:[1,0]
	v_pk_mul_f32 v[40:41], v[52:53], v[60:61]
	v_pk_mul_f32 v[44:45], v[52:53], v[44:45]
	v_pk_mul_f32 v[56:57], v[54:55], v[42:43] op_sel_hi:[1,0] neg_lo:[0,1] neg_hi:[0,1]
	v_pk_mul_f32 v[54:55], v[64:65], v[42:43] op_sel_hi:[1,0] neg_lo:[0,1] neg_hi:[0,1]
	v_pk_mul_f32 v[66:67], v[74:75], v[42:43] op_sel_hi:[1,0]
	v_fmac_f32_e32 v48, v24, v40
	v_add_f32_e32 v40, v40, v78
	v_add_f32_e32 v43, v44, v79
	v_fmac_f32_e32 v48, v25, v41
	v_add_f32_e32 v40, v41, v40
	v_add_f32_e32 v41, v45, v43
	v_add_f32_dpp v43, v48, v48 row_ror:1 row_mask:0xf bank_mask:0xf bound_ctrl:1
	v_add_f32_dpp v40, v40, v40 row_ror:1 row_mask:0xf bank_mask:0xf bound_ctrl:1
	v_add_f32_dpp v41, v41, v41 row_ror:1 row_mask:0xf bank_mask:0xf bound_ctrl:1
	v_add_f32_dpp v43, v43, v43 row_ror:2 row_mask:0xf bank_mask:0xf bound_ctrl:1
	v_add_f32_dpp v45, v40, v40 row_ror:2 row_mask:0xf bank_mask:0xf bound_ctrl:1
	v_add_f32_dpp v41, v41, v41 row_ror:2 row_mask:0xf bank_mask:0xf bound_ctrl:1
	v_add_f32_dpp v40, v43, v43 row_ror:4 row_mask:0xf bank_mask:0xf bound_ctrl:1
	v_add_f32_dpp v43, v45, v45 row_ror:4 row_mask:0xf bank_mask:0xf bound_ctrl:1
	v_add_f32_dpp v44, v41, v41 row_ror:4 row_mask:0xf bank_mask:0xf bound_ctrl:1
	v_mov_b32_e32 v45, v29
	v_mov_b32_e32 v46, v29
	v_mov_b32_e32 v41, v29
	v_pk_add_f32 v[38:39], v[38:39], v[72:73] neg_lo:[0,1] neg_hi:[0,1]
	v_pk_add_f32 v[64:65], v[50:51], 1.0 op_sel_hi:[1,0] neg_lo:[1,0] neg_hi:[1,0]
	v_mov_b32_dpp v45, v44 row_ror:8 row_mask:0xf bank_mask:0xf
	v_mov_b32_dpp v46, v43 row_ror:8 row_mask:0xf bank_mask:0xf
	v_mov_b32_dpp v41, v40 row_ror:8 row_mask:0xf bank_mask:0xf
	v_pk_fma_f32 v[38:39], v[8:9], v[38:39], v[72:73]
	v_pk_fma_f32 v[36:37], v[6:7], v[36:37], v[70:71]
	v_pk_mul_f32 v[50:51], v[76:77], 1.0 op_sel_hi:[1,0]
	v_pk_mul_f32 v[52:53], v[52:53], 1.0 op_sel_hi:[1,0]
	ds_write_b128 v129, v[62:65]
	ds_write_b128 v129, v[58:61] offset:256
	ds_write_b128 v129, v[54:57] offset:512
	ds_write_b128 v129, v[66:69] offset:768
	ds_write_b128 v129, v[50:53] offset:1024
	ds_write_b128 v129, v[36:39] offset:1280
	s_and_saveexec_b64 s[44:45], s[4:5]
	s_mov_b64 s[84:85], s[56:57]
	v_add_f32_e32 v36, v44, v45
	v_mul_f32_e32 v36, v36, v42
	v_add_f32_e32 v37, v43, v46
	ds_write_b64 v128, v[36:37] offset:1536
	s_or_b64 exec, exec, s[44:45]
	s_cmp_lt_u32 s71, 64
	s_cselect_b64 s[44:45], -1, 0
	s_and_b64 s[44:45], s[4:5], s[44:45]
	s_xor_b64 s[52:53], s[44:45], -1
	v_mov_b64_e32 v[100:101], s[14:15]
	s_and_saveexec_b64 s[56:57], s[52:53]
	s_xor_b64 s[52:53], exec, s[56:57]
	v_mov_b64_e32 v[100:101], s[14:15]
	s_andn2_saveexec_b64 s[52:53], s[52:53]
	s_cbranch_execz .LBB0_1105
	v_lshlrev_b32_e32 v38, 6, v139
	v_mov_b32_e32 v39, v29
	v_lshlrev_b32_e32 v36, 6, v1
	v_mov_b32_e32 v37, v29
	s_lshl_b32 s14, s14, 2
	v_lshl_add_u64 v[38:39], s[12:13], 0, v[38:39]
	v_add_f32_e32 v33, v33, v49
	v_lshl_add_u64 v[36:37], s[12:13], 0, v[36:37]
	v_lshl_add_u64 v[38:39], v[38:39], 0, s[14:15]
	v_lshl_add_u64 v[36:37], v[36:37], 0, s[14:15]
	v_add_f32_e32 v1, v40, v41
	global_store_dword v[38:39], v33, off
	global_store_dword v[36:37], v1, off

; #define LAS __attribute__((address_space(3)))
; __device__ __forceinline__ float scan_prepare(const ScanRegs& R, const u32x2 qr_, const u32x2 qk_, const u32x2 qv_, LAS float* slot, int cq, const f32x4 mur, const f32x4 muk, const f32x4 muv, const f32x4 kkc, const f32x4 kac, const f32x4 rkc) {
;     float pr[4], pk[4], pv[4], qr[4], qk[4], qv[4], av[4], om[4];
;     unpack4(R.pr, pr); unpack4(R.pk, pk); unpack4(R.pv, pv); unpack4(qr_, qr); unpack4(qk_, qk); unpack4(qv_, qv); unpack4(R.as, av);
;     om[0] = f16_to_f((unsigned short)(R.wl.x & 0xffffu)); om[1] = f16_to_f((unsigned short)(R.wl.x >> 16)); om[2] = f16_to_f((unsigned short)(R.wl.y & 0xffffu)); om[3] = f16_to_f((unsigned short)(R.wl.y >> 16));
;     float rr[4], vv[4], kn[4], k2[4], dec[4], bu[4];
;     float ssq = 0.f, bon = 0.f, c1 = 0.f, c2 = 0.f;
; #pragma unroll
;     for (int j = 0; j < 4; ++j) {
;         rr[j] = pr[j] + (qr[j] - pr[j]) * mur[j]; const float kk0 = pk[j] + (qk[j] - pk[j]) * muk[j]; vv[j] = pv[j] + (qv[j] - pv[j]) * muv[j];
;         dec[j] = 1.0f - om[j];
;         kn[j] = kk0 * kkc[j]; ssq += kn[j] * kn[j];
;         k2[j] = kk0 * (1.0f + (av[j] - 1.0f) * kac[j]);
;         const float t = rr[j] * k2[j]; bon += t * rkc[j]; c2 += t;
;         bu[j] = kn[j] * av[j]; c1 += bu[j] * rr[j];
;     }
;     ssq += dpp_f<0x121>(ssq); bon += dpp_f<0x121>(bon); c1 += dpp_f<0x121>(c1); c2 += dpp_f<0x121>(c2);
;     ssq += dpp_f<0x122>(ssq); bon += dpp_f<0x122>(bon); c1 += dpp_f<0x122>(c1); c2 += dpp_f<0x122>(c2);
;     ssq += dpp_f<0x124>(ssq); bon += dpp_f<0x124>(bon); c1 += dpp_f<0x124>(c1); c2 += dpp_f<0x124>(c2);
;     ssq += dpp_f<0x128>(ssq); bon += dpp_f<0x128>(bon); c1 += dpp_f<0x128>(c1); c2 += dpp_f<0x128>(c2);
;     const float inv = __builtin_amdgcn_rsqf(fmaxf(ssq, 1e-24f));
;     f32x4 o_al, o_be, o_wr;
; #pragma unroll
;     for (int j = 0; j < 4; ++j) { o_al[j] = -(kn[j] * inv); o_be[j] = bu[j] * inv; o_wr[j] = dec[j] * rr[j]; }
;     LAS f32x4* s4 = (LAS f32x4*)slot;
;     s4[cq] = (f32x4){dec[0], dec[1], dec[2], dec[3]}; s4[16 + cq] = (f32x4){k2[0], k2[1], k2[2], k2[3]}; s4[32 + cq] = o_al; s4[48 + cq] = o_be; s4[64 + cq] = o_wr;
;     s4[80 + cq] = (f32x4){vv[0], vv[1], vv[2], vv[3]};
;     if (cq == 0) *(LAS f32x2*)(slot + 384) = (f32x2){c1 * inv, c2};
;     return bon;
; }
.LBB0_1109:
	s_waitcnt vmcnt(8)
	v_lshlrev_b32_e32 v108, 16, v46
	v_and_b32_e32 v109, 0xffff0000, v46
	v_lshlrev_b32_e32 v110, 16, v38
	v_and_b32_e32 v111, 0xffff0000, v38
	v_pk_add_f32 v[110:111], v[110:111], v[108:109] neg_lo:[0,1] neg_hi:[0,1]
	v_lshlrev_b32_e32 v140, 16, v39
	v_pk_fma_f32 v[144:145], v[6:7], v[110:111], v[108:109]
	v_lshlrev_b32_e32 v110, 16, v47
	v_and_b32_e32 v111, 0xffff0000, v47
	v_and_b32_e32 v141, 0xffff0000, v39
	v_pk_add_f32 v[140:141], v[140:141], v[110:111] neg_lo:[0,1] neg_hi:[0,1]
	v_lshlrev_b32_e32 v118, 16, v40
	v_and_b32_e32 v119, 0xffff0000, v40
	v_pk_fma_f32 v[146:147], v[8:9], v[140:141], v[110:111]
	v_lshlrev_b32_e32 v140, 16, v34
	v_and_b32_e32 v141, 0xffff0000, v34
	s_waitcnt vmcnt(3)
	v_lshlrev_b32_e32 v142, 16, v48
	v_and_b32_e32 v143, 0xffff0000, v48
	v_pk_add_f32 v[140:141], v[140:141], v[118:119] neg_lo:[0,1] neg_hi:[0,1]
	v_pk_add_f32 v[148:149], v[142:143], -1.0 op_sel_hi:[1,0]
	v_pk_fma_f32 v[140:141], v[2:3], v[140:141], v[118:119]
	v_pk_fma_f32 v[148:149], v[18:19], v[148:149], 1.0 op_sel_hi:[1,1,0]
	v_pk_mul_f32 v[154:155], v[14:15], v[140:141]
	v_pk_mul_f32 v[148:149], v[148:149], v[140:141]
	v_cvt_f32_f16_sdwa v141, v44 dst_sel:DWORD dst_unused:UNUSED_PAD src0_sel:WORD_1
	v_cvt_f32_f16_e32 v140, v44
	v_lshlrev_b32_e32 v114, 16, v36
	v_and_b32_e32 v115, 0xffff0000, v36
	v_lshlrev_b32_e32 v156, 16, v42
	v_and_b32_e32 v157, 0xffff0000, v42
	v_pk_add_f32 v[152:153], v[140:141], 1.0 op_sel_hi:[1,0] neg_lo:[1,0] neg_hi:[1,0]
	v_pk_add_f32 v[140:141], v[156:157], v[114:115] neg_lo:[0,1] neg_hi:[0,1]
	v_lshlrev_b32_e32 v116, 16, v41
	v_pk_fma_f32 v[164:165], v[10:11], v[140:141], v[114:115]
	v_and_b32_e32 v117, 0xffff0000, v41
	v_pk_mul_f32 v[140:141], v[164:165], v[148:149]
	v_pk_mul_f32 v[150:151], v[154:155], v[154:155]
	v_fma_f32 v33, v22, v140, 0
	v_add_f32_e32 v28, 0, v140
	v_fmac_f32_e32 v33, v23, v141
	v_add_f32_e32 v168, v141, v28
	v_lshlrev_b32_e32 v140, 16, v35
	v_and_b32_e32 v141, 0xffff0000, v35
	v_pk_add_f32 v[140:141], v[140:141], v[116:117] neg_lo:[0,1] neg_hi:[0,1]
	v_add_f32_e32 v28, v150, v151
	v_pk_fma_f32 v[140:141], v[4:5], v[140:141], v[116:117]
	v_pk_mul_f32 v[142:143], v[154:155], v[142:143]
	v_pk_mul_f32 v[158:159], v[16:17], v[140:141]
	v_pk_mul_f32 v[156:157], v[164:165], v[142:143]
	v_pk_mul_f32 v[160:161], v[158:159], v[158:159]
	v_add_f32_e32 v81, 0, v156
	v_add_f32_e32 v28, v160, v28
	v_add_f32_e32 v28, v161, v28
	v_add_f32_e32 v81, v157, v81
	v_lshlrev_b32_e32 v156, 16, v49
	v_add_f32_dpp v28, v28, v28 row_ror:1 row_mask:0xf bank_mask:0xf bound_ctrl:1
	v_and_b32_e32 v157, 0xffff0000, v49
	v_lshlrev_b32_e32 v112, 16, v37
	v_add_f32_dpp v28, v28, v28 row_ror:2 row_mask:0xf bank_mask:0xf bound_ctrl:1
	v_and_b32_e32 v113, 0xffff0000, v37
	v_pk_add_f32 v[162:163], v[156:157], -1.0 op_sel_hi:[1,0]
	v_add_f32_dpp v28, v28, v28 row_ror:4 row_mask:0xf bank_mask:0xf bound_ctrl:1
	v_pk_fma_f32 v[150:151], v[20:21], v[162:163], 1.0 op_sel_hi:[1,1,0]
	v_pk_mul_f32 v[164:165], v[164:165], 1.0 op_sel_hi:[1,0]
	v_add_f32_dpp v28, v28, v28 row_ror:8 row_mask:0xf bank_mask:0xf bound_ctrl:1
	v_max_f32_e32 v28, 0x179abe15, v28
	v_rsq_f32_e32 v28, v28
	v_pk_mul_f32 v[150:151], v[150:151], v[140:141]
	v_pk_mul_f32 v[140:141], v[158:159], v[156:157]
	v_pk_mul_f32 v[160:161], v[142:143], v[28:29] op_sel_hi:[1,0]
	v_lshlrev_b32_e32 v142, 16, v43
	v_and_b32_e32 v143, 0xffff0000, v43
	v_pk_add_f32 v[142:143], v[142:143], v[112:113] neg_lo:[0,1] neg_hi:[0,1]
	v_pk_mul_f32 v[162:163], v[140:141], v[28:29] op_sel_hi:[1,0]
	v_pk_fma_f32 v[166:167], v[12:13], v[142:143], v[112:113]
	v_pk_mul_f32 v[156:157], v[154:155], v[28:29] op_sel_hi:[1,0] neg_lo:[0,1] neg_hi:[0,1]
	v_pk_mul_f32 v[142:143], v[166:167], v[150:151]
	v_pk_mul_f32 v[140:141], v[166:167], v[140:141]
	v_fmac_f32_e32 v33, v24, v142
	v_add_f32_e32 v142, v142, v168
	v_add_f32_e32 v81, v140, v81
	v_cvt_f32_f16_sdwa v155, v45 dst_sel:DWORD dst_unused:UNUSED_PAD src0_sel:WORD_1
	v_cvt_f32_f16_e32 v154, v45
	v_fmac_f32_e32 v33, v25, v143
	v_add_f32_e32 v140, v143, v142
	v_add_f32_e32 v81, v141, v81
	v_add_f32_dpp v33, v33, v33 row_ror:1 row_mask:0xf bank_mask:0xf bound_ctrl:1
	v_add_f32_dpp v140, v140, v140 row_ror:1 row_mask:0xf bank_mask:0xf bound_ctrl:1
	v_add_f32_dpp v81, v81, v81 row_ror:1 row_mask:0xf bank_mask:0xf bound_ctrl:1
	v_add_f32_dpp v33, v33, v33 row_ror:2 row_mask:0xf bank_mask:0xf bound_ctrl:1
	v_add_f32_dpp v140, v140, v140 row_ror:2 row_mask:0xf bank_mask:0xf bound_ctrl:1
	v_add_f32_dpp v81, v81, v81 row_ror:2 row_mask:0xf bank_mask:0xf bound_ctrl:1
	v_add_f32_dpp v33, v33, v33 row_ror:4 row_mask:0xf bank_mask:0xf bound_ctrl:1
	v_add_f32_dpp v140, v140, v140 row_ror:4 row_mask:0xf bank_mask:0xf bound_ctrl:1
	v_add_f32_dpp v141, v81, v81 row_ror:4 row_mask:0xf bank_mask:0xf bound_ctrl:1
	v_mov_b32_e32 v142, 0
	v_mov_b32_e32 v143, 0
	v_mov_b32_e32 v81, 0
	v_pk_add_f32 v[154:155], v[154:155], 1.0 op_sel_hi:[1,0] neg_lo:[1,0] neg_hi:[1,0]
	v_mov_b32_dpp v142, v141 row_ror:8 row_mask:0xf bank_mask:0xf
	v_mov_b32_dpp v143, v140 row_ror:8 row_mask:0xf bank_mask:0xf
	v_mov_b32_dpp v81, v33 row_ror:8 row_mask:0xf bank_mask:0xf
	v_pk_mul_f32 v[158:159], v[158:159], v[28:29] op_sel_hi:[1,0] neg_lo:[0,1] neg_hi:[0,1]
	v_pk_mul_f32 v[166:167], v[166:167], 1.0 op_sel_hi:[1,0]
	ds_write_b128 v127, v[152:155] offset:50176
	ds_write_b128 v127, v[148:151] offset:50432
	ds_write_b128 v127, v[156:159] offset:50688
	ds_write_b128 v127, v[160:163] offset:50944
	ds_write_b128 v127, v[164:167] offset:51200
	ds_write_b128 v127, v[144:147] offset:51456
	s_and_saveexec_b64 s[52:53], s[4:5]
	v_add_f32_e32 v141, v141, v142
	v_mul_f32_e32 v142, v141, v28
	v_add_f32_e32 v143, v140, v143
	ds_write_b64 v126, v[142:143] offset:51712
	s_or_b64 exec, exec, s[52:53]
	s_waitcnt vmcnt(17)
; #define LAS __attribute__((address_space(3)))
; __device__ __forceinline__ float scan_prepare(const ScanRegs& R, const u32x2 qr_, const u32x2 qk_, const u32x2 qv_, LAS float* slot, int cq, const f32x4 mur, const f32x4 muk, const f32x4 muv, const f32x4 kkc, const f32x4 kac, const f32x4 rkc) {
;     float pr[4], pk[4], pv[4], qr[4], qk[4], qv[4], av[4], om[4];
;     unpack4(R.pr, pr); unpack4(R.pk, pk); unpack4(R.pv, pv); unpack4(qr_, qr); unpack4(qk_, qk); unpack4(qv_, qv); unpack4(R.as, av);
;     om[0] = f16_to_f((unsigned short)(R.wl.x & 0xffffu)); om[1] = f16_to_f((unsigned short)(R.wl.x >> 16)); om[2] = f16_to_f((unsigned short)(R.wl.y & 0xffffu)); om[3] = f16_to_f((unsigned short)(R.wl.y >> 16));
;     float rr[4], vv[4], kn[4], k2[4], dec[4], bu[4];
;     float ssq = 0.f, bon = 0.f, c1 = 0.f, c2 = 0.f;
; #pragma unroll
;     for (int j = 0; j < 4; ++j) {
;         rr[j] = pr[j] + (qr[j] - pr[j]) * mur[j]; const float kk0 = pk[j] + (qk[j] - pk[j]) * muk[j]; vv[j] = pv[j] + (qv[j] - pv[j]) * muv[j];
;         dec[j] = 1.0f - om[j];
;         kn[j] = kk0 * kkc[j]; ssq += kn[j] * kn[j];
;         k2[j] = kk0 * (1.0f + (av[j] - 1.0f) * kac[j]);
;         const float t = rr[j] * k2[j]; bon += t * rkc[j]; c2 += t;
;         bu[j] = kn[j] * av[j]; c1 += bu[j] * rr[j];
;     }
;     ssq += dpp_f<0x121>(ssq); bon += dpp_f<0x121>(bon); c1 += dpp_f<0x121>(c1); c2 += dpp_f<0x121>(c2);
;     ssq += dpp_f<0x122>(ssq); bon += dpp_f<0x122>(bon); c1 += dpp_f<0x122>(c1); c2 += dpp_f<0x122>(c2);
;     ssq += dpp_f<0x124>(ssq); bon += dpp_f<0x124>(bon); c1 += dpp_f<0x124>(c1); c2 += dpp_f<0x124>(c2);
;     ssq += dpp_f<0x128>(ssq); bon += dpp_f<0x128>(bon); c1 += dpp_f<0x128>(c1); c2 += dpp_f<0x128>(c2);
;     const float inv = __builtin_amdgcn_rsqf(fmaxf(ssq, 1e-24f));
;     f32x4 o_al, o_be, o_wr;
; #pragma unroll
;     for (int j = 0; j < 4; ++j) { o_al[j] = -(kn[j] * inv); o_be[j] = bu[j] * inv; o_wr[j] = dec[j] * rr[j]; }
;     LAS f32x4* s4 = (LAS f32x4*)slot;
;     s4[cq] = (f32x4){dec[0], dec[1], dec[2], dec[3]}; s4[16 + cq] = (f32x4){k2[0], k2[1], k2[2], k2[3]}; s4[32 + cq] = o_al; s4[48 + cq] = o_be; s4[64 + cq] = o_wr;
;     s4[80 + cq] = (f32x4){vv[0], vv[1], vv[2], vv[3]};
;     if (cq == 0) *(LAS f32x2*)(slot + 384) = (f32x2){c1 * inv, c2};
;     return bon;
; }
	v_lshlrev_b32_e32 v140, 16, v50
	v_and_b32_e32 v141, 0xffff0000, v50
	s_waitcnt vmcnt(2)
	v_lshlrev_b32_e32 v142, 16, v58
	v_and_b32_e32 v143, 0xffff0000, v58
	v_pk_add_f32 v[118:119], v[118:119], v[140:141] neg_lo:[0,1] neg_hi:[0,1]
	v_lshlrev_b32_e32 v150, 16, v59
	v_pk_fma_f32 v[118:119], v[2:3], v[118:119], v[140:141]
	v_pk_add_f32 v[140:141], v[142:143], -1.0 op_sel_hi:[1,0]
	v_pk_mul_f32 v[146:147], v[14:15], v[118:119]
	v_pk_fma_f32 v[140:141], v[18:19], v[140:141], 1.0 op_sel_hi:[1,1,0]
	v_pk_mul_f32 v[152:153], v[146:147], v[142:143]
	v_pk_mul_f32 v[140:141], v[140:141], v[118:119]
	v_cvt_f32_f16_sdwa v119, v52 dst_sel:DWORD dst_unused:UNUSED_PAD src0_sel:WORD_1
	v_cvt_f32_f16_e32 v118, v52
	s_waitcnt vmcnt(6)
	v_lshlrev_b32_e32 v142, 16, v82
	v_and_b32_e32 v143, 0xffff0000, v82
	v_pk_add_f32 v[114:115], v[114:115], v[142:143] neg_lo:[0,1] neg_hi:[0,1]
	v_pk_add_f32 v[144:145], v[118:119], 1.0 op_sel_hi:[1,0] neg_lo:[1,0] neg_hi:[1,0]
	v_pk_fma_f32 v[118:119], v[10:11], v[114:115], v[142:143]
	v_pk_mul_f32 v[148:149], v[146:147], v[146:147]
	v_pk_mul_f32 v[114:115], v[118:119], v[140:141]
	v_pk_mul_f32 v[142:143], v[118:119], v[152:153]
	v_fma_f32 v156, v22, v114, 0
	v_add_f32_e32 v28, 0, v114
	v_add_f32_e32 v114, 0, v142
	v_fmac_f32_e32 v156, v23, v115
	v_add_f32_e32 v157, v115, v28
	v_add_f32_e32 v164, v143, v114
	v_lshlrev_b32_e32 v114, 16, v51
	v_and_b32_e32 v115, 0xffff0000, v51
	v_pk_add_f32 v[116:117], v[116:117], v[114:115] neg_lo:[0,1] neg_hi:[0,1]
	v_add_f32_e32 v28, v148, v149
	v_pk_fma_f32 v[114:115], v[4:5], v[116:117], v[114:115]
	v_and_b32_e32 v151, 0xffff0000, v59
	v_pk_mul_f32 v[116:117], v[16:17], v[114:115]
	v_pk_add_f32 v[154:155], v[150:151], -1.0 op_sel_hi:[1,0]
	v_pk_mul_f32 v[142:143], v[116:117], v[116:117]
	s_waitcnt vmcnt(5)
	v_lshlrev_b32_e32 v160, 16, v88
	v_add_f32_e32 v28, v142, v28
	v_add_f32_e32 v28, v143, v28
	v_pk_fma_f32 v[142:143], v[20:21], v[154:155], 1.0 op_sel_hi:[1,1,0]
	v_and_b32_e32 v161, 0xffff0000, v88
	v_add_f32_dpp v28, v28, v28 row_ror:1 row_mask:0xf bank_mask:0xf bound_ctrl:1
	v_pk_mul_f32 v[142:143], v[142:143], v[114:115]
	v_pk_mul_f32 v[114:115], v[116:117], v[150:151]
	v_add_f32_dpp v28, v28, v28 row_ror:2 row_mask:0xf bank_mask:0xf bound_ctrl:1
	v_lshlrev_b32_e32 v162, 16, v89
	v_and_b32_e32 v163, 0xffff0000, v89
	v_add_f32_dpp v28, v28, v28 row_ror:4 row_mask:0xf bank_mask:0xf bound_ctrl:1
	v_pk_add_f32 v[108:109], v[108:109], v[160:161] neg_lo:[0,1] neg_hi:[0,1]
	v_pk_add_f32 v[110:111], v[110:111], v[162:163] neg_lo:[0,1] neg_hi:[0,1]
	v_add_f32_dpp v28, v28, v28 row_ror:8 row_mask:0xf bank_mask:0xf bound_ctrl:1
	v_max_f32_e32 v28, 0x179abe15, v28
	v_rsq_f32_e32 v28, v28
	v_pk_fma_f32 v[110:111], v[8:9], v[110:111], v[162:163]
	v_pk_fma_f32 v[108:109], v[6:7], v[108:109], v[160:161]
	v_pk_mul_f32 v[150:151], v[116:117], v[28:29] op_sel_hi:[1,0] neg_lo:[0,1] neg_hi:[0,1]
	v_lshlrev_b32_e32 v116, 16, v83
	v_and_b32_e32 v117, 0xffff0000, v83
	v_pk_add_f32 v[112:113], v[112:113], v[116:117] neg_lo:[0,1] neg_hi:[0,1]
	v_pk_mul_f32 v[154:155], v[114:115], v[28:29] op_sel_hi:[1,0]
	v_pk_fma_f32 v[158:159], v[12:13], v[112:113], v[116:117]
	v_pk_mul_f32 v[148:149], v[146:147], v[28:29] op_sel_hi:[1,0] neg_lo:[0,1] neg_hi:[0,1]
	v_pk_mul_f32 v[112:113], v[158:159], v[142:143]
	v_pk_mul_f32 v[114:115], v[158:159], v[114:115]
	v_fmac_f32_e32 v156, v24, v112
	v_add_f32_e32 v112, v112, v157
	v_add_f32_e32 v114, v114, v164
	v_cvt_f32_f16_sdwa v147, v53 dst_sel:DWORD dst_unused:UNUSED_PAD src0_sel:WORD_1
	v_cvt_f32_f16_e32 v146, v53
	v_fmac_f32_e32 v156, v25, v113
	v_add_f32_e32 v112, v113, v112
	v_add_f32_e32 v113, v115, v114
	v_add_f32_dpp v114, v156, v156 row_ror:1 row_mask:0xf bank_mask:0xf bound_ctrl:1
	v_add_f32_dpp v112, v112, v112 row_ror:1 row_mask:0xf bank_mask:0xf bound_ctrl:1
	v_add_f32_dpp v113, v113, v113 row_ror:1 row_mask:0xf bank_mask:0xf bound_ctrl:1
	v_add_f32_dpp v114, v114, v114 row_ror:2 row_mask:0xf bank_mask:0xf bound_ctrl:1
	v_add_f32_dpp v116, v112, v112 row_ror:2 row_mask:0xf bank_mask:0xf bound_ctrl:1
	v_add_f32_dpp v113, v113, v113 row_ror:2 row_mask:0xf bank_mask:0xf bound_ctrl:1
	v_add_f32_dpp v112, v114, v114 row_ror:4 row_mask:0xf bank_mask:0xf bound_ctrl:1
	v_add_f32_dpp v114, v116, v116 row_ror:4 row_mask:0xf bank_mask:0xf bound_ctrl:1
	v_add_f32_dpp v115, v113, v113 row_ror:4 row_mask:0xf bank_mask:0xf bound_ctrl:1
	v_mov_b32_e32 v116, 0
	v_mov_b32_e32 v117, 0
	v_mov_b32_e32 v113, 0
	v_pk_add_f32 v[146:147], v[146:147], 1.0 op_sel_hi:[1,0] neg_lo:[1,0] neg_hi:[1,0]
	v_mov_b32_dpp v116, v115 row_ror:8 row_mask:0xf bank_mask:0xf
	v_mov_b32_dpp v117, v114 row_ror:8 row_mask:0xf bank_mask:0xf
	v_mov_b32_dpp v113, v112 row_ror:8 row_mask:0xf bank_mask:0xf
	v_pk_mul_f32 v[152:153], v[152:153], v[28:29] op_sel_hi:[1,0]
	v_pk_mul_f32 v[156:157], v[118:119], 1.0 op_sel_hi:[1,0]
	v_pk_mul_f32 v[158:159], v[158:159], 1.0 op_sel_hi:[1,0]
	ds_write_b128 v129, v[144:147] offset:50176
	ds_write_b128 v129, v[140:143] offset:50432
	ds_write_b128 v129, v[148:151] offset:50688
	ds_write_b128 v129, v[152:155] offset:50944
	ds_write_b128 v129, v[156:159] offset:51200
	ds_write_b128 v129, v[108:111] offset:51456
	s_and_saveexec_b64 s[52:53], s[4:5]
	s_cbranch_execz .LBB0_1121
	v_add_f32_e32 v108, v115, v116
	v_mul_f32_e32 v108, v108, v28
	v_add_f32_e32 v109, v114, v117
	ds_write_b64 v128, v[108:109] offset:51712
	s_or_b64 exec, exec, s[52:53]
	s_and_saveexec_b64 s[52:53], s[44:45]
	s_cbranch_execnz .LBB0_1122

; #define LAS __attribute__((address_space(3)))
; __device__ __forceinline__ float scan_prepare(const ScanRegs& R, const u32x2 qr_, const u32x2 qk_, const u32x2 qv_, LAS float* slot, int cq, const f32x4 mur, const f32x4 muk, const f32x4 muv, const f32x4 kkc, const f32x4 kac, const f32x4 rkc) {
;     float pr[4], pk[4], pv[4], qr[4], qk[4], qv[4], av[4], om[4];
;     unpack4(R.pr, pr); unpack4(R.pk, pk); unpack4(R.pv, pv); unpack4(qr_, qr); unpack4(qk_, qk); unpack4(qv_, qv); unpack4(R.as, av);
;     om[0] = f16_to_f((unsigned short)(R.wl.x & 0xffffu)); om[1] = f16_to_f((unsigned short)(R.wl.x >> 16)); om[2] = f16_to_f((unsigned short)(R.wl.y & 0xffffu)); om[3] = f16_to_f((unsigned short)(R.wl.y >> 16));
;     float rr[4], vv[4], kn[4], k2[4], dec[4], bu[4];
;     float ssq = 0.f, bon = 0.f, c1 = 0.f, c2 = 0.f;
; #pragma unroll
;     for (int j = 0; j < 4; ++j) {
;         rr[j] = pr[j] + (qr[j] - pr[j]) * mur[j]; const float kk0 = pk[j] + (qk[j] - pk[j]) * muk[j]; vv[j] = pv[j] + (qv[j] - pv[j]) * muv[j];
;         dec[j] = 1.0f - om[j];
;         kn[j] = kk0 * kkc[j]; ssq += kn[j] * kn[j];
;         k2[j] = kk0 * (1.0f + (av[j] - 1.0f) * kac[j]);
;         const float t = rr[j] * k2[j]; bon += t * rkc[j]; c2 += t;
;         bu[j] = kn[j] * av[j]; c1 += bu[j] * rr[j];
;     }
;     ssq += dpp_f<0x121>(ssq); bon += dpp_f<0x121>(bon); c1 += dpp_f<0x121>(c1); c2 += dpp_f<0x121>(c2);
;     ssq += dpp_f<0x122>(ssq); bon += dpp_f<0x122>(bon); c1 += dpp_f<0x122>(c1); c2 += dpp_f<0x122>(c2);
;     ssq += dpp_f<0x124>(ssq); bon += dpp_f<0x124>(bon); c1 += dpp_f<0x124>(c1); c2 += dpp_f<0x124>(c2);
;     ssq += dpp_f<0x128>(ssq); bon += dpp_f<0x128>(bon); c1 += dpp_f<0x128>(c1); c2 += dpp_f<0x128>(c2);
;     const float inv = __builtin_amdgcn_rsqf(fmaxf(ssq, 1e-24f));
;     f32x4 o_al, o_be, o_wr;
; #pragma unroll
;     for (int j = 0; j < 4; ++j) { o_al[j] = -(kn[j] * inv); o_be[j] = bu[j] * inv; o_wr[j] = dec[j] * rr[j]; }
;     LAS f32x4* s4 = (LAS f32x4*)slot;
;     s4[cq] = (f32x4){dec[0], dec[1], dec[2], dec[3]}; s4[16 + cq] = (f32x4){k2[0], k2[1], k2[2], k2[3]}; s4[32 + cq] = o_al; s4[48 + cq] = o_be; s4[64 + cq] = o_wr;
;     s4[80 + cq] = (f32x4){vv[0], vv[1], vv[2], vv[3]};
;     if (cq == 0) *(LAS f32x2*)(slot + 384) = (f32x2){c1 * inv, c2};
;     return bon;
; }
.LBB0_1115:
	v_add_u32_e32 v28, v120, v130
	s_waitcnt lgkmcnt(0)
	s_barrier
	ds_read_b128 v[108:111], v28
	v_lshl_add_u64 v[112:113], s[92:93], 0, v[100:101]
	v_add_co_u32_e32 v112, vcc, s68, v112
	s_cmpk_gt_u32 s14, 0xfd
	s_waitcnt lgkmcnt(0)
	v_add_f32_e32 v28, v108, v109
	v_add_f32_e32 v33, v110, v111
	v_add_f32_e32 v28, v28, v33
	v_bfe_u32 v33, v28, 16, 1
	v_add3_u32 v28, v28, v33, s67
	v_addc_co_u32_e32 v113, vcc, 0, v113, vcc
	global_store_short_d16_hi v[112:113], v28, off
	v_add_u32_e32 v28, v120, v131
	ds_read_b128 v[108:111], v28
	s_cselect_b64 s[52:53], -1, 0
	s_and_b64 vcc, exec, s[52:53]
	s_waitcnt lgkmcnt(0)
	v_add_f32_e32 v28, v108, v109
	v_add_f32_e32 v33, v110, v111
	v_add_f32_e32 v28, v28, v33
	v_bfe_u32 v33, v28, 16, 1
	v_add3_u32 v28, v28, v33, s67
	global_store_short_d16_hi v[112:113], v28, off offset:2048
	s_cbranch_vccnz .LBB0_1106
	v_lshlrev_b32_e32 v108, 16, v76
	v_and_b32_e32 v109, 0xffff0000, v76
	v_lshlrev_b32_e32 v110, 16, v62
	v_and_b32_e32 v111, 0xffff0000, v62
	v_pk_add_f32 v[110:111], v[110:111], v[108:109] neg_lo:[0,1] neg_hi:[0,1]
	v_lshlrev_b32_e32 v140, 16, v63
	v_pk_fma_f32 v[144:145], v[6:7], v[110:111], v[108:109]
	v_lshlrev_b32_e32 v110, 16, v77
	v_and_b32_e32 v111, 0xffff0000, v77
	v_and_b32_e32 v141, 0xffff0000, v63
	v_pk_add_f32 v[140:141], v[140:141], v[110:111] neg_lo:[0,1] neg_hi:[0,1]
	v_lshlrev_b32_e32 v118, 16, v64
	v_and_b32_e32 v119, 0xffff0000, v64
	v_pk_fma_f32 v[146:147], v[8:9], v[140:141], v[110:111]
	v_lshlrev_b32_e32 v140, 16, v54
	v_and_b32_e32 v141, 0xffff0000, v54
	s_waitcnt vmcnt(3)
	v_lshlrev_b32_e32 v142, 16, v86
	v_and_b32_e32 v143, 0xffff0000, v86
	v_pk_add_f32 v[140:141], v[140:141], v[118:119] neg_lo:[0,1] neg_hi:[0,1]
	v_pk_add_f32 v[148:149], v[142:143], -1.0 op_sel_hi:[1,0]
	v_pk_fma_f32 v[140:141], v[2:3], v[140:141], v[118:119]
	v_pk_fma_f32 v[148:149], v[18:19], v[148:149], 1.0 op_sel_hi:[1,1,0]
	v_pk_mul_f32 v[154:155], v[14:15], v[140:141]
	v_pk_mul_f32 v[148:149], v[140:141], v[148:149]
	v_cvt_f32_f16_sdwa v141, v72 dst_sel:DWORD dst_unused:UNUSED_PAD src0_sel:WORD_1
	v_cvt_f32_f16_e32 v140, v72
	v_lshlrev_b32_e32 v114, 16, v56
	v_and_b32_e32 v115, 0xffff0000, v56
	v_lshlrev_b32_e32 v156, 16, v68
	v_and_b32_e32 v157, 0xffff0000, v68
	v_pk_add_f32 v[152:153], v[140:141], 1.0 op_sel_hi:[1,0] neg_lo:[1,0] neg_hi:[1,0]
	v_pk_add_f32 v[140:141], v[156:157], v[114:115] neg_lo:[0,1] neg_hi:[0,1]
	v_lshlrev_b32_e32 v116, 16, v65
	v_pk_fma_f32 v[164:165], v[10:11], v[140:141], v[114:115]
	v_and_b32_e32 v117, 0xffff0000, v65
	v_pk_mul_f32 v[140:141], v[164:165], v[148:149]
	v_pk_mul_f32 v[150:151], v[154:155], v[154:155]
	v_fma_f32 v33, v22, v140, 0
	v_add_f32_e32 v28, 0, v140
	v_fmac_f32_e32 v33, v23, v141
	v_add_f32_e32 v168, v141, v28
	v_lshlrev_b32_e32 v140, 16, v55
	v_and_b32_e32 v141, 0xffff0000, v55
	v_pk_add_f32 v[140:141], v[140:141], v[116:117] neg_lo:[0,1] neg_hi:[0,1]
	v_add_f32_e32 v28, v150, v151
	v_pk_fma_f32 v[140:141], v[4:5], v[140:141], v[116:117]
	v_pk_mul_f32 v[142:143], v[154:155], v[142:143]
	v_pk_mul_f32 v[158:159], v[16:17], v[140:141]
	v_pk_mul_f32 v[156:157], v[164:165], v[142:143]
	v_pk_mul_f32 v[160:161], v[158:159], v[158:159]
	v_add_f32_e32 v81, 0, v156
	v_add_f32_e32 v28, v160, v28
	v_add_f32_e32 v28, v161, v28
	v_add_f32_e32 v81, v157, v81
	v_lshlrev_b32_e32 v156, 16, v87
	v_add_f32_dpp v28, v28, v28 row_ror:1 row_mask:0xf bank_mask:0xf bound_ctrl:1
	v_and_b32_e32 v157, 0xffff0000, v87
	v_lshlrev_b32_e32 v112, 16, v57
	v_add_f32_dpp v28, v28, v28 row_ror:2 row_mask:0xf bank_mask:0xf bound_ctrl:1
	v_and_b32_e32 v113, 0xffff0000, v57
	v_pk_add_f32 v[162:163], v[156:157], -1.0 op_sel_hi:[1,0]
	v_add_f32_dpp v28, v28, v28 row_ror:4 row_mask:0xf bank_mask:0xf bound_ctrl:1
	v_pk_fma_f32 v[150:151], v[20:21], v[162:163], 1.0 op_sel_hi:[1,1,0]
	v_pk_mul_f32 v[164:165], v[164:165], 1.0 op_sel_hi:[1,0]
	v_add_f32_dpp v28, v28, v28 row_ror:8 row_mask:0xf bank_mask:0xf bound_ctrl:1
	v_max_f32_e32 v28, 0x179abe15, v28
	v_rsq_f32_e32 v28, v28
	v_pk_mul_f32 v[150:151], v[140:141], v[150:151]
	v_pk_mul_f32 v[140:141], v[158:159], v[156:157]
	v_pk_mul_f32 v[160:161], v[142:143], v[28:29] op_sel_hi:[1,0]
	v_lshlrev_b32_e32 v142, 16, v69
	v_and_b32_e32 v143, 0xffff0000, v69
	v_pk_add_f32 v[142:143], v[142:143], v[112:113] neg_lo:[0,1] neg_hi:[0,1]
	v_pk_mul_f32 v[162:163], v[140:141], v[28:29] op_sel_hi:[1,0]
	v_pk_fma_f32 v[166:167], v[12:13], v[142:143], v[112:113]
	v_pk_mul_f32 v[156:157], v[154:155], v[28:29] op_sel_hi:[1,0] neg_lo:[0,1] neg_hi:[0,1]
	v_pk_mul_f32 v[142:143], v[166:167], v[150:151]
	v_pk_mul_f32 v[140:141], v[166:167], v[140:141]
	v_fmac_f32_e32 v33, v24, v142
	v_add_f32_e32 v142, v142, v168
	v_add_f32_e32 v81, v140, v81
	v_cvt_f32_f16_sdwa v155, v73 dst_sel:DWORD dst_unused:UNUSED_PAD src0_sel:WORD_1
	v_cvt_f32_f16_e32 v154, v73
	v_fmac_f32_e32 v33, v25, v143
	v_add_f32_e32 v140, v143, v142
	v_add_f32_e32 v81, v141, v81
	v_add_f32_dpp v33, v33, v33 row_ror:1 row_mask:0xf bank_mask:0xf bound_ctrl:1
	v_add_f32_dpp v140, v140, v140 row_ror:1 row_mask:0xf bank_mask:0xf bound_ctrl:1
	v_add_f32_dpp v81, v81, v81 row_ror:1 row_mask:0xf bank_mask:0xf bound_ctrl:1
	v_add_f32_dpp v33, v33, v33 row_ror:2 row_mask:0xf bank_mask:0xf bound_ctrl:1
	v_add_f32_dpp v140, v140, v140 row_ror:2 row_mask:0xf bank_mask:0xf bound_ctrl:1
	v_add_f32_dpp v81, v81, v81 row_ror:2 row_mask:0xf bank_mask:0xf bound_ctrl:1
	v_add_f32_dpp v33, v33, v33 row_ror:4 row_mask:0xf bank_mask:0xf bound_ctrl:1
	v_add_f32_dpp v140, v140, v140 row_ror:4 row_mask:0xf bank_mask:0xf bound_ctrl:1
	v_add_f32_dpp v141, v81, v81 row_ror:4 row_mask:0xf bank_mask:0xf bound_ctrl:1
	v_mov_b32_e32 v142, 0
	v_mov_b32_e32 v143, 0
	v_mov_b32_e32 v81, 0
	v_pk_add_f32 v[154:155], v[154:155], 1.0 op_sel_hi:[1,0] neg_lo:[1,0] neg_hi:[1,0]
	v_mov_b32_dpp v142, v141 row_ror:8 row_mask:0xf bank_mask:0xf
	v_mov_b32_dpp v143, v140 row_ror:8 row_mask:0xf bank_mask:0xf
	v_mov_b32_dpp v81, v33 row_ror:8 row_mask:0xf bank_mask:0xf
	v_pk_mul_f32 v[158:159], v[158:159], v[28:29] op_sel_hi:[1,0] neg_lo:[0,1] neg_hi:[0,1]
	v_pk_mul_f32 v[166:167], v[166:167], 1.0 op_sel_hi:[1,0]
	ds_write_b128 v127, v[152:155]
	ds_write_b128 v127, v[148:151] offset:256
	ds_write_b128 v127, v[156:159] offset:512
	ds_write_b128 v127, v[160:163] offset:768
	ds_write_b128 v127, v[164:167] offset:1024
	ds_write_b128 v127, v[144:147] offset:1280
	s_and_saveexec_b64 s[56:57], s[4:5]
	v_add_f32_e32 v141, v141, v142
	v_mul_f32_e32 v142, v141, v28
	v_add_f32_e32 v143, v140, v143
	ds_write_b64 v126, v[142:143] offset:1536
	s_or_b64 exec, exec, s[56:57]
	s_waitcnt vmcnt(4)
; #define LAS __attribute__((address_space(3)))
; __device__ __forceinline__ float scan_prepare(const ScanRegs& R, const u32x2 qr_, const u32x2 qk_, const u32x2 qv_, LAS float* slot, int cq, const f32x4 mur, const f32x4 muk, const f32x4 muv, const f32x4 kkc, const f32x4 kac, const f32x4 rkc) {
;     float pr[4], pk[4], pv[4], qr[4], qk[4], qv[4], av[4], om[4];
;     unpack4(R.pr, pr); unpack4(R.pk, pk); unpack4(R.pv, pv); unpack4(qr_, qr); unpack4(qk_, qk); unpack4(qv_, qv); unpack4(R.as, av);
;     om[0] = f16_to_f((unsigned short)(R.wl.x & 0xffffu)); om[1] = f16_to_f((unsigned short)(R.wl.x >> 16)); om[2] = f16_to_f((unsigned short)(R.wl.y & 0xffffu)); om[3] = f16_to_f((unsigned short)(R.wl.y >> 16));
;     float rr[4], vv[4], kn[4], k2[4], dec[4], bu[4];
;     float ssq = 0.f, bon = 0.f, c1 = 0.f, c2 = 0.f;
; #pragma unroll
;     for (int j = 0; j < 4; ++j) {
;         rr[j] = pr[j] + (qr[j] - pr[j]) * mur[j]; const float kk0 = pk[j] + (qk[j] - pk[j]) * muk[j]; vv[j] = pv[j] + (qv[j] - pv[j]) * muv[j];
;         dec[j] = 1.0f - om[j];
;         kn[j] = kk0 * kkc[j]; ssq += kn[j] * kn[j];
;         k2[j] = kk0 * (1.0f + (av[j] - 1.0f) * kac[j]);
;         const float t = rr[j] * k2[j]; bon += t * rkc[j]; c2 += t;
;         bu[j] = kn[j] * av[j]; c1 += bu[j] * rr[j];
;     }
;     ssq += dpp_f<0x121>(ssq); bon += dpp_f<0x121>(bon); c1 += dpp_f<0x121>(c1); c2 += dpp_f<0x121>(c2);
;     ssq += dpp_f<0x122>(ssq); bon += dpp_f<0x122>(bon); c1 += dpp_f<0x122>(c1); c2 += dpp_f<0x122>(c2);
;     ssq += dpp_f<0x124>(ssq); bon += dpp_f<0x124>(bon); c1 += dpp_f<0x124>(c1); c2 += dpp_f<0x124>(c2);
;     ssq += dpp_f<0x128>(ssq); bon += dpp_f<0x128>(bon); c1 += dpp_f<0x128>(c1); c2 += dpp_f<0x128>(c2);
;     const float inv = __builtin_amdgcn_rsqf(fmaxf(ssq, 1e-24f));
;     f32x4 o_al, o_be, o_wr;
; #pragma unroll
;     for (int j = 0; j < 4; ++j) { o_al[j] = -(kn[j] * inv); o_be[j] = bu[j] * inv; o_wr[j] = dec[j] * rr[j]; }
;     LAS f32x4* s4 = (LAS f32x4*)slot;
;     s4[cq] = (f32x4){dec[0], dec[1], dec[2], dec[3]}; s4[16 + cq] = (f32x4){k2[0], k2[1], k2[2], k2[3]}; s4[32 + cq] = o_al; s4[48 + cq] = o_be; s4[64 + cq] = o_wr;
;     s4[80 + cq] = (f32x4){vv[0], vv[1], vv[2], vv[3]};
;     if (cq == 0) *(LAS f32x2*)(slot + 384) = (f32x2){c1 * inv, c2};
;     return bon;
; }
	v_lshlrev_b32_e32 v140, 16, v96
	v_and_b32_e32 v141, 0xffff0000, v96
	s_waitcnt vmcnt(2)
	v_lshlrev_b32_e32 v142, 16, v102
	v_and_b32_e32 v143, 0xffff0000, v102
	v_pk_add_f32 v[118:119], v[118:119], v[140:141] neg_lo:[0,1] neg_hi:[0,1]
	v_lshlrev_b32_e32 v150, 16, v103
	v_pk_fma_f32 v[118:119], v[2:3], v[118:119], v[140:141]
	v_pk_add_f32 v[140:141], v[142:143], -1.0 op_sel_hi:[1,0]
	v_pk_mul_f32 v[146:147], v[14:15], v[118:119]
	v_pk_fma_f32 v[140:141], v[18:19], v[140:141], 1.0 op_sel_hi:[1,1,0]
	v_pk_mul_f32 v[152:153], v[146:147], v[142:143]
	v_pk_mul_f32 v[140:141], v[140:141], v[118:119]
	v_cvt_f32_f16_sdwa v119, v98 dst_sel:DWORD dst_unused:UNUSED_PAD src0_sel:WORD_1
	v_cvt_f32_f16_e32 v118, v98
	v_lshlrev_b32_e32 v142, 16, v84
	v_and_b32_e32 v143, 0xffff0000, v84
	v_pk_add_f32 v[114:115], v[114:115], v[142:143] neg_lo:[0,1] neg_hi:[0,1]
	v_pk_add_f32 v[144:145], v[118:119], 1.0 op_sel_hi:[1,0] neg_lo:[1,0] neg_hi:[1,0]
	v_pk_fma_f32 v[118:119], v[10:11], v[114:115], v[142:143]
	v_pk_mul_f32 v[148:149], v[146:147], v[146:147]
	v_pk_mul_f32 v[114:115], v[118:119], v[140:141]
	v_pk_mul_f32 v[142:143], v[118:119], v[152:153]
	v_fma_f32 v156, v22, v114, 0
	v_add_f32_e32 v28, 0, v114
	v_add_f32_e32 v114, 0, v142
	v_fmac_f32_e32 v156, v23, v115
	v_add_f32_e32 v157, v115, v28
	v_add_f32_e32 v164, v143, v114
	v_lshlrev_b32_e32 v114, 16, v97
	v_and_b32_e32 v115, 0xffff0000, v97
	v_pk_add_f32 v[116:117], v[116:117], v[114:115] neg_lo:[0,1] neg_hi:[0,1]
	v_add_f32_e32 v28, v148, v149
	v_pk_fma_f32 v[114:115], v[4:5], v[116:117], v[114:115]
	v_and_b32_e32 v151, 0xffff0000, v103
	v_pk_mul_f32 v[116:117], v[16:17], v[114:115]
	v_pk_add_f32 v[154:155], v[150:151], -1.0 op_sel_hi:[1,0]
	v_pk_mul_f32 v[142:143], v[116:117], v[116:117]
	v_lshlrev_b32_e32 v160, 16, v94
	v_add_f32_e32 v28, v142, v28
	v_add_f32_e32 v28, v143, v28
	v_pk_fma_f32 v[142:143], v[20:21], v[154:155], 1.0 op_sel_hi:[1,1,0]
	v_and_b32_e32 v161, 0xffff0000, v94
	v_add_f32_dpp v28, v28, v28 row_ror:1 row_mask:0xf bank_mask:0xf bound_ctrl:1
	v_pk_mul_f32 v[142:143], v[142:143], v[114:115]
	v_pk_mul_f32 v[114:115], v[116:117], v[150:151]
	v_add_f32_dpp v28, v28, v28 row_ror:2 row_mask:0xf bank_mask:0xf bound_ctrl:1
	v_lshlrev_b32_e32 v162, 16, v95
	v_and_b32_e32 v163, 0xffff0000, v95
	v_add_f32_dpp v28, v28, v28 row_ror:4 row_mask:0xf bank_mask:0xf bound_ctrl:1
	v_pk_add_f32 v[108:109], v[108:109], v[160:161] neg_lo:[0,1] neg_hi:[0,1]
	v_pk_add_f32 v[110:111], v[110:111], v[162:163] neg_lo:[0,1] neg_hi:[0,1]
	v_add_f32_dpp v28, v28, v28 row_ror:8 row_mask:0xf bank_mask:0xf bound_ctrl:1
	v_max_f32_e32 v28, 0x179abe15, v28
	v_rsq_f32_e32 v28, v28
	v_pk_fma_f32 v[110:111], v[8:9], v[110:111], v[162:163]
	v_pk_fma_f32 v[108:109], v[6:7], v[108:109], v[160:161]
	v_pk_mul_f32 v[150:151], v[116:117], v[28:29] op_sel_hi:[1,0] neg_lo:[0,1] neg_hi:[0,1]
	v_lshlrev_b32_e32 v116, 16, v85
	v_and_b32_e32 v117, 0xffff0000, v85
	v_pk_add_f32 v[112:113], v[112:113], v[116:117] neg_lo:[0,1] neg_hi:[0,1]
	v_pk_mul_f32 v[154:155], v[114:115], v[28:29] op_sel_hi:[1,0]
	v_pk_fma_f32 v[158:159], v[12:13], v[112:113], v[116:117]
	v_pk_mul_f32 v[148:149], v[146:147], v[28:29] op_sel_hi:[1,0] neg_lo:[0,1] neg_hi:[0,1]
	v_pk_mul_f32 v[112:113], v[158:159], v[142:143]
	v_pk_mul_f32 v[114:115], v[158:159], v[114:115]
	v_fmac_f32_e32 v156, v24, v112
	v_add_f32_e32 v112, v112, v157
	v_add_f32_e32 v114, v114, v164
	v_cvt_f32_f16_sdwa v147, v99 dst_sel:DWORD dst_unused:UNUSED_PAD src0_sel:WORD_1
	v_cvt_f32_f16_e32 v146, v99
	v_fmac_f32_e32 v156, v25, v113
	v_add_f32_e32 v112, v113, v112
	v_add_f32_e32 v113, v115, v114
	v_add_f32_dpp v114, v156, v156 row_ror:1 row_mask:0xf bank_mask:0xf bound_ctrl:1
	v_add_f32_dpp v112, v112, v112 row_ror:1 row_mask:0xf bank_mask:0xf bound_ctrl:1
	v_add_f32_dpp v113, v113, v113 row_ror:1 row_mask:0xf bank_mask:0xf bound_ctrl:1
	v_add_f32_dpp v114, v114, v114 row_ror:2 row_mask:0xf bank_mask:0xf bound_ctrl:1
	v_add_f32_dpp v116, v112, v112 row_ror:2 row_mask:0xf bank_mask:0xf bound_ctrl:1
	v_add_f32_dpp v113, v113, v113 row_ror:2 row_mask:0xf bank_mask:0xf bound_ctrl:1
	v_add_f32_dpp v112, v114, v114 row_ror:4 row_mask:0xf bank_mask:0xf bound_ctrl:1
	v_add_f32_dpp v114, v116, v116 row_ror:4 row_mask:0xf bank_mask:0xf bound_ctrl:1
	v_add_f32_dpp v115, v113, v113 row_ror:4 row_mask:0xf bank_mask:0xf bound_ctrl:1
	v_mov_b32_e32 v116, 0
	v_mov_b32_e32 v117, 0
	v_mov_b32_e32 v113, 0
	v_pk_add_f32 v[146:147], v[146:147], 1.0 op_sel_hi:[1,0] neg_lo:[1,0] neg_hi:[1,0]
	v_mov_b32_dpp v116, v115 row_ror:8 row_mask:0xf bank_mask:0xf
	v_mov_b32_dpp v117, v114 row_ror:8 row_mask:0xf bank_mask:0xf
	v_mov_b32_dpp v113, v112 row_ror:8 row_mask:0xf bank_mask:0xf
	v_pk_mul_f32 v[152:153], v[152:153], v[28:29] op_sel_hi:[1,0]
	v_pk_mul_f32 v[156:157], v[118:119], 1.0 op_sel_hi:[1,0]
	v_pk_mul_f32 v[158:159], v[158:159], 1.0 op_sel_hi:[1,0]
	ds_write_b128 v129, v[144:147]
	ds_write_b128 v129, v[140:143] offset:256
	ds_write_b128 v129, v[148:151] offset:512
	ds_write_b128 v129, v[152:155] offset:768
	ds_write_b128 v129, v[156:159] offset:1024
	ds_write_b128 v129, v[108:111] offset:1280
	s_and_saveexec_b64 s[56:57], s[4:5]
	s_cbranch_execz .LBB0_1123
	v_add_f32_e32 v108, v115, v116
	v_mul_f32_e32 v108, v108, v28
	v_add_f32_e32 v109, v114, v117
	ds_write_b64 v128, v[108:109] offset:1536
	s_or_b64 exec, exec, s[56:57]
	s_and_saveexec_b64 s[56:57], s[44:45]
	s_cbranch_execnz .LBB0_1124
